# peeled last k-step of the GEMM tiles: the second of two back-to-back barriers replaced by a same-size s_nop
# baseline (speedup 1.0000x reference)
; #define MFMA(a, b, c) __builtin_amdgcn_mfma_f32_32x32x16_bf16((a), (b), (c), 0, 0, 0)
; template <bool SWAP, bool SSQ, class AF>
; DI void gemm_main(AF asrc, int m0, const u16* __restrict__ Bw, int ldb, int K, char* smem,
;                   f32x16 (&acc)[4][2], float ssq_eps, float (&rs)[4]) {
;     ...
;   for (int kt = 0; kt < nkt; ++kt) {
;     if (kt + 1 < nkt) gload(kt + 1);
;     __builtin_amdgcn_sched_barrier(0);
;     {
;       bf16x8 ar[3], br[2][2];
;       ar[0] = *(const bf16x8*)(pA);
;       ar[1] = *(const bf16x8*)(pA + 32 * 144);
;       br[0][0] = *(const bf16x8*)(pB);
;       br[0][1] = *(const bf16x8*)(pB + 32 * 144);
;       __builtin_amdgcn_sched_group_barrier(0x100, 4, 0);
; #pragma unroll
;       for (int t = 0; t < 16; ++t) {
;         const int ks = t >> 2, mi = t & 3;
;         if (t + 2 < 16) {
;           ar[(t + 2) % 3] = *(const bf16x8*)(pA + ((t + 2) & 3) * (32 * 144) + ((t + 2) >> 2) * 32);
;           if (mi == 1 && ks + 1 < 4) {
;             br[(ks + 1) & 1][0] = *(const bf16x8*)(pB + (ks + 1) * 32);
;             br[(ks + 1) & 1][1] = *(const bf16x8*)(pB + 32 * 144 + (ks + 1) * 32);
;             __builtin_amdgcn_sched_group_barrier(0x100, 3, 0);
;           } else {
;             __builtin_amdgcn_sched_group_barrier(0x100, 1, 0);
;           }
;         }
;         acc[mi][0] = SWAP ? MFMA(br[ks & 1][0], ar[t % 3], acc[mi][0]) : MFMA(ar[t % 3], br[ks & 1][0], acc[mi][0]);
;         acc[mi][1] = SWAP ? MFMA(br[ks & 1][1], ar[t % 3], acc[mi][1]) : MFMA(ar[t % 3], br[ks & 1][1], acc[mi][1]);
;         __builtin_amdgcn_sched_group_barrier(0x008, 2, 0);
;         if (SSQ) {
;           u32x4 u = __builtin_bit_cast(u32x4, ar[t % 3]);
; #pragma unroll
;           for (int j = 0; j < 4; ++j) rs[mi] = dot2bf(u[j], rs[mi]);
;         }
;       }
;     }
;     __syncthreads();
;     if (kt + 1 < nkt) sstore();
;     __syncthreads();
;   }
.LBB0_250:
	ds_read_b128 v[234:237], v139 offset:13824
	global_load_dwordx4 v[144:147], v184, s[4:5]
	global_load_dwordx4 v[148:151], v246, s[4:5]
	s_waitcnt lgkmcnt(3)
	v_mfma_f32_32x32x16_bf16 v[112:127], v[194:197], v[222:225], v[112:127]
	v_mfma_f32_32x32x16_bf16 v[96:111], v[218:221], v[222:225], v[96:111]
	ds_read_b128 v[222:225], v140 offset:36896
	ds_read_b128 v[238:241], v140 offset:41504
	global_load_dwordx4 v[152:155], v247, s[4:5]
	global_load_dwordx4 v[156:159], v248, s[4:5]
	s_waitcnt lgkmcnt(4)
	v_mfma_f32_32x32x16_bf16 v[80:95], v[194:197], v[226:229], v[80:95]
	v_mfma_f32_32x32x16_bf16 v[64:79], v[218:221], v[226:229], v[64:79]
	ds_read_b128 v[226:229], v139 offset:32
	global_load_dwordx4 v[160:163], v184, s[100:101]
	global_load_dwordx4 v[164:167], v246, s[100:101]
	s_waitcnt lgkmcnt(4)
	v_mfma_f32_32x32x16_bf16 v[48:63], v[194:197], v[230:233], v[48:63]
	v_mfma_f32_32x32x16_bf16 v[32:47], v[218:221], v[230:233], v[32:47]
	ds_read_b128 v[230:233], v139 offset:4640
	global_load_dwordx4 v[168:171], v247, s[100:101]
	global_load_dwordx4 v[172:175], v248, s[100:101]
	s_waitcnt lgkmcnt(4)
	v_mfma_f32_32x32x16_bf16 v[16:31], v[194:197], v[234:237], v[16:31]
	v_mfma_f32_32x32x16_bf16 v[0:15], v[218:221], v[234:237], v[0:15]
	ds_read_b128 v[194:197], v139 offset:9248
	ds_read_b128 v[218:221], v139 offset:13856
	global_load_dwordx4 v[176:179], v184, s[92:93]
	global_load_dwordx4 v[180:183], v184, s[6:7]
	s_waitcnt lgkmcnt(3)
	v_mfma_f32_32x32x16_bf16 v[112:127], v[222:225], v[226:229], v[112:127]
	v_mfma_f32_32x32x16_bf16 v[96:111], v[238:241], v[226:229], v[96:111]
	ds_read_b128 v[226:229], v140 offset:36928
	ds_read_b128 v[202:205], v140 offset:41536
	global_load_dwordx4 v[186:189], v184, s[96:97]
	global_load_dwordx4 v[190:193], v184, vcc
	s_waitcnt lgkmcnt(4)
	v_mfma_f32_32x32x16_bf16 v[80:95], v[222:225], v[230:233], v[80:95]
	v_mfma_f32_32x32x16_bf16 v[64:79], v[238:241], v[230:233], v[64:79]
	ds_read_b128 v[230:233], v139 offset:64
	ds_read_b128 v[206:209], v139 offset:4672
	s_waitcnt lgkmcnt(5)
	v_mfma_f32_32x32x16_bf16 v[48:63], v[222:225], v[194:197], v[48:63]
	v_mfma_f32_32x32x16_bf16 v[32:47], v[238:241], v[194:197], v[32:47]
	ds_read_b128 v[194:197], v139 offset:9280
	s_waitcnt lgkmcnt(5)
	v_mfma_f32_32x32x16_bf16 v[16:31], v[222:225], v[218:221], v[16:31]
	v_mfma_f32_32x32x16_bf16 v[0:15], v[238:241], v[218:221], v[0:15]
	ds_read_b128 v[222:225], v139 offset:13888
	ds_read_b128 v[242:245], v140 offset:36960
	ds_read_b128 v[234:237], v140 offset:41568
	s_waitcnt lgkmcnt(5)
	v_mfma_f32_32x32x16_bf16 v[112:127], v[226:229], v[230:233], v[112:127]
	v_mfma_f32_32x32x16_bf16 v[96:111], v[202:205], v[230:233], v[96:111]
	ds_read_b128 v[218:221], v139 offset:96
	ds_read_b128 v[230:233], v139 offset:4704
	s_waitcnt lgkmcnt(6)
	v_mfma_f32_32x32x16_bf16 v[80:95], v[226:229], v[206:209], v[80:95]
	v_mfma_f32_32x32x16_bf16 v[64:79], v[202:205], v[206:209], v[64:79]
	ds_read_b128 v[238:241], v139 offset:9312
	ds_read_b128 v[206:209], v139 offset:13920
	s_waitcnt lgkmcnt(0)
	s_barrier
	v_mfma_f32_32x32x16_bf16 v[48:63], v[226:229], v[194:197], v[48:63]
	v_mfma_f32_32x32x16_bf16 v[32:47], v[202:205], v[194:197], v[32:47]
	s_waitcnt vmcnt(11)
	ds_write_b128 v138, v[144:147]
	s_waitcnt vmcnt(10)
	ds_write_b128 v138, v[148:151] offset:4608
	s_waitcnt vmcnt(9)
	ds_write_b128 v138, v[152:155] offset:9216
	s_waitcnt vmcnt(8)
	ds_write_b128 v138, v[156:159] offset:13824
	v_mfma_f32_32x32x16_bf16 v[16:31], v[226:229], v[222:225], v[16:31]
	v_mfma_f32_32x32x16_bf16 v[0:15], v[202:205], v[222:225], v[0:15]
	s_waitcnt vmcnt(7)
	ds_write_b128 v138, v[160:163] offset:18432
	s_waitcnt vmcnt(6)
	ds_write_b128 v138, v[164:167] offset:23040
	s_waitcnt vmcnt(5)
	ds_write_b128 v138, v[168:171] offset:27648
	s_waitcnt vmcnt(4)
	ds_write_b128 v138, v[172:175] offset:32256
	v_mfma_f32_32x32x16_bf16 v[112:127], v[242:245], v[218:221], v[112:127]
	v_mfma_f32_32x32x16_bf16 v[96:111], v[234:237], v[218:221], v[96:111]
	s_waitcnt vmcnt(3)
	ds_write_b128 v138, v[176:179] offset:36864
	s_waitcnt vmcnt(2)
	ds_write_b128 v138, v[180:183] offset:41472
	s_waitcnt vmcnt(1)
	ds_write_b128 v138, v[186:189] offset:46080
	s_waitcnt vmcnt(0)
	ds_write_b128 v138, v[190:193] offset:50688
	v_mfma_f32_32x32x16_bf16 v[80:95], v[242:245], v[230:233], v[80:95]
	v_mfma_f32_32x32x16_bf16 v[64:79], v[234:237], v[230:233], v[64:79]
	s_waitcnt lgkmcnt(0)
	s_barrier
	ds_read_b128 v[194:197], v140 offset:36864
	ds_read_b128 v[218:221], v140 offset:41472
	ds_read_b128 v[222:225], v139
	ds_read_b128 v[226:229], v139 offset:4608
	ds_read_b128 v[230:233], v139 offset:9216
	v_mfma_f32_32x32x16_bf16 v[48:63], v[242:245], v[238:241], v[48:63]
	v_mfma_f32_32x32x16_bf16 v[32:47], v[234:237], v[238:241], v[32:47]
	v_mfma_f32_32x32x16_bf16 v[16:31], v[242:245], v[206:209], v[16:31]
	v_mfma_f32_32x32x16_bf16 v[0:15], v[234:237], v[206:209], v[0:15]
	s_add_u32 s92, s92, 0x80
	s_addc_u32 s93, s93, 0
	s_add_u32 s96, s96, 0x80
	s_addc_u32 s97, s97, 0
	s_add_u32 vcc_lo, vcc_lo, 0x80
	s_addc_u32 vcc_hi, vcc_hi, 0
	s_add_u32 s6, s6, 0x80
	s_addc_u32 s7, s7, 0
	s_add_u32 s4, s4, 0x80
	s_addc_u32 s5, s5, 0
	s_add_u32 s100, s100, 0x80
	s_addc_u32 s101, s101, 0
	s_add_i32 s20, s20, -1
	s_cmp_lg_u32 s20, 0
	s_cbranch_scc1 .LBB0_250
; #define MFMA(a, b, c) __builtin_amdgcn_mfma_f32_32x32x16_bf16((a), (b), (c), 0, 0, 0)
; template <bool SWAP, bool SSQ, class AF>
; DI void gemm_main(AF asrc, int m0, const u16* __restrict__ Bw, int ldb, int K, char* smem,
;                   f32x16 (&acc)[4][2], float ssq_eps, float (&rs)[4]) {
;     ...
;   for (int kt = 0; kt < nkt; ++kt) {
;     if (kt + 1 < nkt) gload(kt + 1);
;     __builtin_amdgcn_sched_barrier(0);
;     {
;       bf16x8 ar[3], br[2][2];
;       ar[0] = *(const bf16x8*)(pA);
;       ar[1] = *(const bf16x8*)(pA + 32 * 144);
;       br[0][0] = *(const bf16x8*)(pB);
;       br[0][1] = *(const bf16x8*)(pB + 32 * 144);
;       __builtin_amdgcn_sched_group_barrier(0x100, 4, 0);
; #pragma unroll
;       for (int t = 0; t < 16; ++t) {
;         const int ks = t >> 2, mi = t & 3;
;         if (t + 2 < 16) {
;           ar[(t + 2) % 3] = *(const bf16x8*)(pA + ((t + 2) & 3) * (32 * 144) + ((t + 2) >> 2) * 32);
;           if (mi == 1 && ks + 1 < 4) {
;             br[(ks + 1) & 1][0] = *(const bf16x8*)(pB + (ks + 1) * 32);
;             br[(ks + 1) & 1][1] = *(const bf16x8*)(pB + 32 * 144 + (ks + 1) * 32);
;             __builtin_amdgcn_sched_group_barrier(0x100, 3, 0);
;           } else {
;             __builtin_amdgcn_sched_group_barrier(0x100, 1, 0);
;           }
;         }
;         acc[mi][0] = SWAP ? MFMA(br[ks & 1][0], ar[t % 3], acc[mi][0]) : MFMA(ar[t % 3], br[ks & 1][0], acc[mi][0]);
;         acc[mi][1] = SWAP ? MFMA(br[ks & 1][1], ar[t % 3], acc[mi][1]) : MFMA(ar[t % 3], br[ks & 1][1], acc[mi][1]);
;         __builtin_amdgcn_sched_group_barrier(0x008, 2, 0);
;         if (SSQ) {
;           u32x4 u = __builtin_bit_cast(u32x4, ar[t % 3]);
; #pragma unroll
;           for (int j = 0; j < 4; ++j) rs[mi] = dot2bf(u[j], rs[mi]);
;         }
;       }
;     }
;     __syncthreads();
;     if (kt + 1 < nkt) sstore();
;     __syncthreads();
;   }
; DI void phase_upproj(const Params& p, const GroupP& g, int l, char* smem, int vb) {
;     ...
;       {
;         const float* sq = p.rowsq + (size_t)(l * 2 + (isq ? 0 : 1)) * 50432 + g.seq0 + m0 + wm * 128 + lr;
;         const float invK = 1.f / (float)Kd;
; #pragma unroll
;         for (int mi = 0; mi < 4; ++mi) rs[mi] = __builtin_amdgcn_rsqf(sq[mi * 32] * invK + 1e-6f);
;       }
	ds_read_b128 v[144:147], v140 offset:36864
	ds_read_b128 v[156:159], v140 offset:41472
	ds_read_b128 v[148:151], v139
	ds_read_b128 v[152:155], v139 offset:4608
	ds_read_b128 v[160:163], v139 offset:9216
	v_cndmask_b32_e64 v138, 0, 1, s[90:91]
	v_readlane_b32 s5, v253, 7
	v_readfirstlane_b32 s4, v138
	s_or_b32 s4, s23, s4
	s_waitcnt lgkmcnt(2)
	v_mfma_f32_32x32x16_bf16 v[112:127], v[144:147], v[148:151], v[112:127]
	s_mul_i32 s4, s4, 0x31400
	s_add_u32 s6, s5, s4
	v_readlane_b32 s4, v254, 41
	s_addc_u32 s7, s4, 0
	s_lshl_b64 s[4:5], s[88:89], 2
	s_add_u32 s4, s6, s4
	s_addc_u32 s5, s7, s5
	v_mfma_f32_32x32x16_bf16 v[96:111], v[156:159], v[148:151], v[96:111]
	ds_read_b128 v[164:167], v140 offset:36896
	ds_read_b128 v[168:171], v140 offset:41504
	ds_read_b128 v[148:151], v139 offset:13824
	s_add_u32 s4, s4, s12
	s_addc_u32 s5, s5, s13
	v_cvt_f32_u32_e32 v142, s87
	v_readlane_b32 s6, v254, 36
	s_waitcnt lgkmcnt(4)
	v_mfma_f32_32x32x16_bf16 v[80:95], v[144:147], v[152:155], v[80:95]
	s_mov_b32 s87, s22
	v_readlane_b32 s7, v254, 37
	v_mfma_f32_32x32x16_bf16 v[64:79], v[156:159], v[152:155], v[64:79]
	ds_read_b128 v[152:155], v139 offset:32
	s_waitcnt lgkmcnt(4)
	v_mfma_f32_32x32x16_bf16 v[48:63], v[144:147], v[160:163], v[48:63]
	v_mfma_f32_32x32x16_bf16 v[32:47], v[156:159], v[160:163], v[32:47]
	ds_read_b128 v[160:163], v139 offset:4640
	s_waitcnt lgkmcnt(2)
	v_mfma_f32_32x32x16_bf16 v[16:31], v[144:147], v[148:151], v[16:31]
	v_mfma_f32_32x32x16_bf16 v[0:15], v[156:159], v[148:151], v[0:15]
	ds_read_b128 v[144:147], v139 offset:9248
	s_waitcnt lgkmcnt(2)
	v_mfma_f32_32x32x16_bf16 v[112:127], v[164:167], v[152:155], v[112:127]
	v_mfma_f32_32x32x16_bf16 v[96:111], v[168:171], v[152:155], v[96:111]
	ds_read_b128 v[152:155], v140 offset:36928
	ds_read_b128 v[156:159], v140 offset:41536
	ds_read_b128 v[148:151], v139 offset:13856
	s_waitcnt lgkmcnt(4)
	v_mfma_f32_32x32x16_bf16 v[80:95], v[164:167], v[160:163], v[80:95]
	v_mfma_f32_32x32x16_bf16 v[64:79], v[168:171], v[160:163], v[64:79]
	ds_read_b128 v[160:163], v139 offset:64
	s_waitcnt lgkmcnt(4)
	v_mfma_f32_32x32x16_bf16 v[48:63], v[164:167], v[144:147], v[48:63]
	v_mfma_f32_32x32x16_bf16 v[32:47], v[168:171], v[144:147], v[32:47]
	ds_read_b128 v[144:147], v139 offset:4672
	s_waitcnt lgkmcnt(2)
	v_mfma_f32_32x32x16_bf16 v[16:31], v[164:167], v[148:151], v[16:31]
	v_mfma_f32_32x32x16_bf16 v[0:15], v[168:171], v[148:151], v[0:15]
	ds_read_b128 v[148:151], v139 offset:9280
	s_waitcnt lgkmcnt(2)
	v_mfma_f32_32x32x16_bf16 v[112:127], v[152:155], v[160:163], v[112:127]
	v_mfma_f32_32x32x16_bf16 v[96:111], v[156:159], v[160:163], v[96:111]
	ds_read_b128 v[164:167], v140 offset:36960
	ds_read_b128 v[168:171], v140 offset:41568
	ds_read_b128 v[160:163], v139 offset:13888
	s_waitcnt lgkmcnt(4)
	v_mfma_f32_32x32x16_bf16 v[80:95], v[152:155], v[144:147], v[80:95]
	v_mfma_f32_32x32x16_bf16 v[64:79], v[156:159], v[144:147], v[64:79]
	ds_read_b128 v[144:147], v139 offset:96
	s_waitcnt lgkmcnt(4)
	v_mfma_f32_32x32x16_bf16 v[48:63], v[152:155], v[148:151], v[48:63]
	v_mfma_f32_32x32x16_bf16 v[32:47], v[156:159], v[148:151], v[32:47]
	ds_read_b128 v[148:151], v139 offset:4704
	s_waitcnt lgkmcnt(2)
	v_mfma_f32_32x32x16_bf16 v[16:31], v[152:155], v[160:163], v[16:31]
	v_mfma_f32_32x32x16_bf16 v[0:15], v[156:159], v[160:163], v[0:15]
	ds_read_b128 v[152:155], v139 offset:9312
	s_waitcnt lgkmcnt(2)
	v_mfma_f32_32x32x16_bf16 v[112:127], v[164:167], v[144:147], v[112:127]
	v_mfma_f32_32x32x16_bf16 v[96:111], v[168:171], v[144:147], v[96:111]
	ds_read_b128 v[144:147], v139 offset:13920
	s_waitcnt lgkmcnt(0)
	s_barrier
; template <bool SWAP, bool SSQ, class AF>
; DI void gemm_main(AF asrc, int m0, const u16* __restrict__ Bw, int ldb, int K, char* smem,
;                   f32x16 (&acc)[4][2], float ssq_eps, float (&rs)[4]) {
;     ...
;     __syncthreads();
;     if (kt + 1 < nkt) sstore();
;     __syncthreads();
; DI void phase_upproj(const Params& p, const GroupP& g, int l, char* smem, int vb) {
;     ...
;       {
;         const float* sq = p.rowsq + (size_t)(l * 2 + (isq ? 0 : 1)) * 50432 + g.seq0 + m0 + wm * 128 + lr;
;         const float invK = 1.f / (float)Kd;
; #pragma unroll
;         for (int mi = 0; mi < 4; ++mi) rs[mi] = __builtin_amdgcn_rsqf(sq[mi * 32] * invK + 1e-6f);
;       }
;       const int nw0 = n0 + wn * 64;
;       if (isq) {
;         const int head = nw0 / 192, w = nw0 - head * 192;
; #pragma unroll
;         for (int mi = 0; mi < 4; ++mi) {
;           int m = m0 + wm * 128 + mi * 32 + lr;
;           float r = rs[mi];
;           if (w == 128) {
;             int b = m / g.Lp, t = m - b * g.Lp;
;             f32x16 a0 = acc[mi][0], a1 = acc[mi][1];
; #pragma unroll
;             for (int i = 0; i < 16; ++i) { a0[i] *= r; a1[i] *= r; }
;             rope_store(a0, a1, p.rope + t * 32, g.q + (long)m * 1536 + nw0, lh);
;           } else {
;             u16* qp = g.q + (long)m * 1536 + nw0;
; #pragma unroll
;             for (int ni = 0; ni < 2; ++ni)
; #pragma unroll
;               for (int pr = 0; pr < 2; ++pr)
;                 store_bf8_pair(qp + ni * 32 + 16 * pr, lh, acc[mi][ni][8 * pr] * r, acc[mi][ni][8 * pr + 1] * r,
;                                acc[mi][ni][8 * pr + 2] * r, acc[mi][ni][8 * pr + 3] * r, acc[mi][ni][8 * pr + 4] * r,
;                                acc[mi][ni][8 * pr + 5] * r, acc[mi][ni][8 * pr + 6] * r, acc[mi][ni][8 * pr + 7] * r);
	s_nop 0
	global_load_dword v138, v143, s[4:5]
	global_load_dword v139, v143, s[4:5] offset:128
	global_load_dword v140, v143, s[4:5] offset:256
	v_mfma_f32_32x32x16_bf16 v[80:95], v[164:167], v[148:151], v[80:95]
	v_mfma_f32_32x32x16_bf16 v[64:79], v[168:171], v[148:151], v[64:79]
	global_load_dword v148, v143, s[4:5] offset:384
	v_div_scale_f32 v149, s[4:5], v142, v142, 1.0
	v_rcp_f32_e32 v150, v149
	s_mov_b64 s[4:5], -1
	v_mfma_f32_32x32x16_bf16 v[48:63], v[164:167], v[152:155], v[48:63]
	v_mfma_f32_32x32x16_bf16 v[32:47], v[168:171], v[152:155], v[32:47]
	v_mfma_f32_32x32x16_bf16 v[16:31], v[164:167], v[144:147], v[16:31]
	v_mfma_f32_32x32x16_bf16 v[0:15], v[168:171], v[144:147], v[0:15]
	v_fma_f32 v144, -v149, v150, 1.0
	v_fmac_f32_e32 v150, v144, v150
	v_div_scale_f32 v144, vcc, 1.0, v142, 1.0
	v_mul_f32_e32 v145, v144, v150
	v_fma_f32 v146, -v149, v145, v144
	v_fmac_f32_e32 v145, v146, v150
	v_fma_f32 v144, -v149, v145, v144
	v_div_fmas_f32 v144, v144, v150, v145
	v_div_fixup_f32 v145, v144, v142, 1.0
	v_add_u32_e32 v146, s88, v129
	s_andn2_b64 vcc, exec, s[8:9]
	s_waitcnt vmcnt(3)
	v_fmaak_f32 v138, v145, v138, 0x358637bd
	v_rsq_f32_e32 v144, v138
	s_waitcnt vmcnt(2)
	v_fmaak_f32 v138, v145, v139, 0x358637bd
	v_rsq_f32_e32 v142, v138
	s_waitcnt vmcnt(1)
	v_fmaak_f32 v138, v145, v140, 0x358637bd
	v_rsq_f32_e32 v140, v138
	s_waitcnt vmcnt(0)
	v_fmaak_f32 v138, v145, v148, 0x358637bd
	v_rsq_f32_e32 v138, v138
	s_cbranch_vccnz .LBB0_264
	s_or_b32 s88, s19, s15
	s_mul_hi_i32 s4, s88, 0x2aaaaaab
	s_lshr_b32 s5, s4, 31
	s_lshr_b32 s4, s4, 5
	s_add_i32 s4, s4, s5
	s_mulk_i32 s4, 0xc0
	s_sub_i32 s4, s88, s4
	s_cmpk_lg_i32 s4, 0x80
	s_cselect_b64 s[4:5], -1, 0
	s_ashr_i32 s89, s88, 31
	s_mov_b64 s[6:7], -1
	s_and_b64 vcc, exec, s[4:5]
	v_lshlrev_b32_e32 v184, 1, v130
	s_cbranch_vccz .LBB0_254
	v_readlane_b32 s6, v254, 36
	v_readlane_b32 s7, v254, 37
	s_load_dwordx16 s[36:51], s[6:7], 0xf8
	s_movk_i32 s6, 0xc00
	v_pk_mul_f32 v[150:151], v[114:115], v[144:145] op_sel_hi:[1,0]
	v_pk_mul_f32 v[154:155], v[116:117], v[144:145] op_sel_hi:[1,0]
	v_pk_mul_f32 v[156:157], v[118:119], v[144:145] op_sel_hi:[1,0]
	s_waitcnt lgkmcnt(0)
	v_mov_b64_e32 v[148:149], s[38:39]
	v_mad_i64_i32 v[148:149], s[6:7], v146, s6, v[148:149]
	v_lshl_add_u64 v[148:149], s[88:89], 1, v[148:149]
	v_lshl_add_u64 v[152:153], v[148:149], 0, v[184:185]
	v_pk_mul_f32 v[148:149], v[112:113], v[144:145] op_sel_hi:[1,0]
	s_mov_b64 s[6:7], 0
	v_cvt_pk_bf16_f32 v148, v148, v149
	v_cvt_pk_bf16_f32 v149, v150, v151
	v_cvt_pk_bf16_f32 v150, v154, v155
	v_cvt_pk_bf16_f32 v151, v156, v157
	s_nop 0
	v_permlane32_swap_b32_e32 v148, v150
	v_permlane32_swap_b32_e32 v149, v151
	global_store_dwordx4 v[152:153], v[148:151], off
	v_pk_mul_f32 v[154:155], v[124:125], v[144:145] op_sel_hi:[1,0]
	v_pk_mul_f32 v[156:157], v[126:127], v[144:145] op_sel_hi:[1,0]
	v_pk_mul_f32 v[148:149], v[120:121], v[144:145] op_sel_hi:[1,0]
	v_pk_mul_f32 v[150:151], v[122:123], v[144:145] op_sel_hi:[1,0]
	v_cvt_pk_bf16_f32 v148, v148, v149
	v_cvt_pk_bf16_f32 v149, v150, v151
	v_cvt_pk_bf16_f32 v150, v154, v155
	v_cvt_pk_bf16_f32 v151, v156, v157
	s_nop 0
	v_permlane32_swap_b32_e32 v148, v150
	v_permlane32_swap_b32_e32 v149, v151
	global_store_dwordx4 v[152:153], v[148:151], off offset:32
	v_pk_mul_f32 v[154:155], v[100:101], v[144:145] op_sel_hi:[1,0]
	v_pk_mul_f32 v[156:157], v[102:103], v[144:145] op_sel_hi:[1,0]
	v_pk_mul_f32 v[148:149], v[96:97], v[144:145] op_sel_hi:[1,0]
	v_pk_mul_f32 v[150:151], v[98:99], v[144:145] op_sel_hi:[1,0]
	v_cvt_pk_bf16_f32 v148, v148, v149
	v_cvt_pk_bf16_f32 v149, v150, v151
	v_cvt_pk_bf16_f32 v150, v154, v155
	v_cvt_pk_bf16_f32 v151, v156, v157
	s_nop 0
	v_permlane32_swap_b32_e32 v148, v150
	v_permlane32_swap_b32_e32 v149, v151
	global_store_dwordx4 v[152:153], v[148:151], off offset:64
	v_pk_mul_f32 v[154:155], v[108:109], v[144:145] op_sel_hi:[1,0]
	v_pk_mul_f32 v[156:157], v[110:111], v[144:145] op_sel_hi:[1,0]
	v_pk_mul_f32 v[148:149], v[104:105], v[144:145] op_sel_hi:[1,0]
	v_pk_mul_f32 v[150:151], v[106:107], v[144:145] op_sel_hi:[1,0]
	v_cvt_pk_bf16_f32 v148, v148, v149
	v_cvt_pk_bf16_f32 v149, v150, v151
	v_cvt_pk_bf16_f32 v150, v154, v155
	v_cvt_pk_bf16_f32 v151, v156, v157
	s_nop 0
	v_permlane32_swap_b32_e32 v148, v150
	v_permlane32_swap_b32_e32 v149, v151
	global_store_dwordx4 v[152:153], v[148:151], off offset:96

; #define MFMA(a, b, c) __builtin_amdgcn_mfma_f32_32x32x16_bf16((a), (b), (c), 0, 0, 0)
; template <bool SWAP, bool SSQ, class AF>
; DI void gemm_main(AF asrc, int m0, const u16* __restrict__ Bw, int ldb, int K, char* smem,
;                   f32x16 (&acc)[4][2], float ssq_eps, float (&rs)[4]) {
;     ...
;   for (int kt = 0; kt < nkt; ++kt) {
;     if (kt + 1 < nkt) gload(kt + 1);
;     __builtin_amdgcn_sched_barrier(0);
;     {
;       bf16x8 ar[3], br[2][2];
;       ar[0] = *(const bf16x8*)(pA);
;       ar[1] = *(const bf16x8*)(pA + 32 * 144);
;       br[0][0] = *(const bf16x8*)(pB);
;       br[0][1] = *(const bf16x8*)(pB + 32 * 144);
;       __builtin_amdgcn_sched_group_barrier(0x100, 4, 0);
; #pragma unroll
;       for (int t = 0; t < 16; ++t) {
;         const int ks = t >> 2, mi = t & 3;
;         if (t + 2 < 16) {
;           ar[(t + 2) % 3] = *(const bf16x8*)(pA + ((t + 2) & 3) * (32 * 144) + ((t + 2) >> 2) * 32);
;           if (mi == 1 && ks + 1 < 4) {
;             br[(ks + 1) & 1][0] = *(const bf16x8*)(pB + (ks + 1) * 32);
;             br[(ks + 1) & 1][1] = *(const bf16x8*)(pB + 32 * 144 + (ks + 1) * 32);
;             __builtin_amdgcn_sched_group_barrier(0x100, 3, 0);
;           } else {
;             __builtin_amdgcn_sched_group_barrier(0x100, 1, 0);
;           }
;         }
;         acc[mi][0] = SWAP ? MFMA(br[ks & 1][0], ar[t % 3], acc[mi][0]) : MFMA(ar[t % 3], br[ks & 1][0], acc[mi][0]);
;         acc[mi][1] = SWAP ? MFMA(br[ks & 1][1], ar[t % 3], acc[mi][1]) : MFMA(ar[t % 3], br[ks & 1][1], acc[mi][1]);
;         __builtin_amdgcn_sched_group_barrier(0x008, 2, 0);
;         if (SSQ) {
;           u32x4 u = __builtin_bit_cast(u32x4, ar[t % 3]);
; #pragma unroll
;           for (int j = 0; j < 4; ++j) rs[mi] = dot2bf(u[j], rs[mi]);
;         }
;       }
;     }
;     __syncthreads();
;     if (kt + 1 < nkt) sstore();
;     __syncthreads();
;   }
.LBB0_455:
	ds_read_b128 v[238:241], v137 offset:13824
	global_load_dwordx4 v[144:147], v198, s[34:35]
	global_load_dwordx4 v[150:153], v199, s[34:35]
	s_waitcnt lgkmcnt(3)
	v_mfma_f32_32x32x16_bf16 v[112:127], v[218:221], v[226:229], v[112:127]
	v_mfma_f32_32x32x16_bf16 v[96:111], v[222:225], v[226:229], v[96:111]
	ds_read_b128 v[226:229], v142 offset:36896
	ds_read_b128 v[242:245], v142 offset:41504
	global_load_dwordx4 v[154:157], v217, s[34:35]
	global_load_dwordx4 v[158:161], v250, s[34:35]
	s_waitcnt lgkmcnt(4)
	v_mfma_f32_32x32x16_bf16 v[80:95], v[218:221], v[230:233], v[80:95]
	v_mfma_f32_32x32x16_bf16 v[64:79], v[222:225], v[230:233], v[64:79]
	ds_read_b128 v[230:233], v137 offset:32
	global_load_dwordx4 v[162:165], v198, s[36:37]
	global_load_dwordx4 v[166:169], v199, s[36:37]
	s_waitcnt lgkmcnt(4)
	v_mfma_f32_32x32x16_bf16 v[48:63], v[218:221], v[234:237], v[48:63]
	v_mfma_f32_32x32x16_bf16 v[32:47], v[222:225], v[234:237], v[32:47]
	ds_read_b128 v[234:237], v137 offset:4640
	global_load_dwordx4 v[170:173], v217, s[36:37]
	global_load_dwordx4 v[174:177], v250, s[36:37]
	s_waitcnt lgkmcnt(4)
	v_mfma_f32_32x32x16_bf16 v[16:31], v[218:221], v[238:241], v[16:31]
	v_mfma_f32_32x32x16_bf16 v[0:15], v[222:225], v[238:241], v[0:15]
	ds_read_b128 v[218:221], v137 offset:9248
	ds_read_b128 v[222:225], v137 offset:13856
	global_load_dwordx4 v[178:181], v198, s[100:101]
	global_load_dwordx4 v[186:189], v199, s[100:101]
	s_waitcnt lgkmcnt(3)
	v_mfma_f32_32x32x16_bf16 v[112:127], v[226:229], v[230:233], v[112:127]
	v_mfma_f32_32x32x16_bf16 v[96:111], v[242:245], v[230:233], v[96:111]
	ds_read_b128 v[230:233], v142 offset:36928
	ds_read_b128 v[202:205], v142 offset:41536
	global_load_dwordx4 v[190:193], v217, s[100:101]
	global_load_dwordx4 v[194:197], v250, s[100:101]
	s_waitcnt lgkmcnt(4)
	v_mfma_f32_32x32x16_bf16 v[80:95], v[226:229], v[234:237], v[80:95]
	v_mfma_f32_32x32x16_bf16 v[64:79], v[242:245], v[234:237], v[64:79]
	ds_read_b128 v[234:237], v137 offset:64
	ds_read_b128 v[206:209], v137 offset:4672
	s_waitcnt lgkmcnt(5)
	v_mfma_f32_32x32x16_bf16 v[48:63], v[226:229], v[218:221], v[48:63]
	v_mfma_f32_32x32x16_bf16 v[32:47], v[242:245], v[218:221], v[32:47]
	ds_read_b128 v[218:221], v137 offset:9280
	s_waitcnt lgkmcnt(5)
	v_mfma_f32_32x32x16_bf16 v[16:31], v[226:229], v[222:225], v[16:31]
	v_mfma_f32_32x32x16_bf16 v[0:15], v[242:245], v[222:225], v[0:15]
	ds_read_b128 v[226:229], v137 offset:13888
	ds_read_b128 v[246:249], v142 offset:36960
	ds_read_b128 v[238:241], v142 offset:41568
	s_waitcnt lgkmcnt(5)
	v_mfma_f32_32x32x16_bf16 v[112:127], v[230:233], v[234:237], v[112:127]
	v_mfma_f32_32x32x16_bf16 v[96:111], v[202:205], v[234:237], v[96:111]
	ds_read_b128 v[222:225], v137 offset:96
	ds_read_b128 v[234:237], v137 offset:4704
	s_waitcnt lgkmcnt(6)
	v_mfma_f32_32x32x16_bf16 v[80:95], v[230:233], v[206:209], v[80:95]
	v_mfma_f32_32x32x16_bf16 v[64:79], v[202:205], v[206:209], v[64:79]
	ds_read_b128 v[242:245], v137 offset:9312
	ds_read_b128 v[206:209], v137 offset:13920
	s_waitcnt lgkmcnt(0)
	s_barrier
	v_mfma_f32_32x32x16_bf16 v[48:63], v[230:233], v[218:221], v[48:63]
	v_mfma_f32_32x32x16_bf16 v[32:47], v[202:205], v[218:221], v[32:47]
	s_waitcnt vmcnt(11)
	ds_write_b128 v136, v[144:147]
	s_waitcnt vmcnt(10)
	ds_write_b128 v136, v[150:153] offset:4608
	s_waitcnt vmcnt(9)
	ds_write_b128 v136, v[154:157] offset:9216
	s_waitcnt vmcnt(8)
	ds_write_b128 v136, v[158:161] offset:13824
	v_mfma_f32_32x32x16_bf16 v[16:31], v[230:233], v[226:229], v[16:31]
	v_mfma_f32_32x32x16_bf16 v[0:15], v[202:205], v[226:229], v[0:15]
	s_waitcnt vmcnt(7)
	ds_write_b128 v136, v[162:165] offset:18432
	s_waitcnt vmcnt(6)
	ds_write_b128 v136, v[166:169] offset:23040
	s_waitcnt vmcnt(5)
	ds_write_b128 v136, v[170:173] offset:27648
	s_waitcnt vmcnt(4)
	ds_write_b128 v136, v[174:177] offset:32256
	v_mfma_f32_32x32x16_bf16 v[112:127], v[246:249], v[222:225], v[112:127]
	v_mfma_f32_32x32x16_bf16 v[96:111], v[238:241], v[222:225], v[96:111]
	s_waitcnt vmcnt(3)
	ds_write_b128 v136, v[178:181] offset:36864
	s_waitcnt vmcnt(2)
	ds_write_b128 v136, v[186:189] offset:41472
	s_waitcnt vmcnt(1)
	ds_write_b128 v136, v[190:193] offset:46080
	s_waitcnt vmcnt(0)
	ds_write_b128 v136, v[194:197] offset:50688
	v_mfma_f32_32x32x16_bf16 v[80:95], v[246:249], v[234:237], v[80:95]
	v_mfma_f32_32x32x16_bf16 v[64:79], v[238:241], v[234:237], v[64:79]
	s_waitcnt lgkmcnt(0)
	s_barrier
	ds_read_b128 v[218:221], v142 offset:36864
	ds_read_b128 v[222:225], v142 offset:41472
	ds_read_b128 v[226:229], v137
	ds_read_b128 v[230:233], v137 offset:4608
	ds_read_b128 v[234:237], v137 offset:9216
	v_mfma_f32_32x32x16_bf16 v[48:63], v[246:249], v[242:245], v[48:63]
	v_mfma_f32_32x32x16_bf16 v[32:47], v[238:241], v[242:245], v[32:47]
	v_mfma_f32_32x32x16_bf16 v[16:31], v[246:249], v[206:209], v[16:31]
	v_mfma_f32_32x32x16_bf16 v[0:15], v[238:241], v[206:209], v[0:15]
	s_add_u32 s34, s34, 0x80
	s_addc_u32 s35, s35, 0
	s_add_u32 s36, s36, 0x80
	s_addc_u32 s37, s37, 0
	s_add_u32 s100, s100, 0x80
	s_addc_u32 s101, s101, 0
	s_add_u32 s12, s12, 0x80
	s_cmpk_lg_i32 s12, 0xf80
	s_cbranch_scc1 .LBB0_455
; #define MFMA(a, b, c) __builtin_amdgcn_mfma_f32_32x32x16_bf16((a), (b), (c), 0, 0, 0)
; template <bool SWAP, bool SSQ, class AF>
; DI void gemm_main(AF asrc, int m0, const u16* __restrict__ Bw, int ldb, int K, char* smem,
;                   f32x16 (&acc)[4][2], float ssq_eps, float (&rs)[4]) {
;     ...
;     {
;       bf16x8 ar[3], br[2][2];
;       ar[0] = *(const bf16x8*)(pA);
;       ar[1] = *(const bf16x8*)(pA + 32 * 144);
;       br[0][0] = *(const bf16x8*)(pB);
;       br[0][1] = *(const bf16x8*)(pB + 32 * 144);
;       __builtin_amdgcn_sched_group_barrier(0x100, 4, 0);
; #pragma unroll
;       for (int t = 0; t < 16; ++t) {
;         const int ks = t >> 2, mi = t & 3;
;         if (t + 2 < 16) {
;           ar[(t + 2) % 3] = *(const bf16x8*)(pA + ((t + 2) & 3) * (32 * 144) + ((t + 2) >> 2) * 32);
;           if (mi == 1 && ks + 1 < 4) {
;             br[(ks + 1) & 1][0] = *(const bf16x8*)(pB + (ks + 1) * 32);
;             br[(ks + 1) & 1][1] = *(const bf16x8*)(pB + 32 * 144 + (ks + 1) * 32);
;             __builtin_amdgcn_sched_group_barrier(0x100, 3, 0);
;           } else {
;             __builtin_amdgcn_sched_group_barrier(0x100, 1, 0);
;           }
;         }
;         acc[mi][0] = SWAP ? MFMA(br[ks & 1][0], ar[t % 3], acc[mi][0]) : MFMA(ar[t % 3], br[ks & 1][0], acc[mi][0]);
;         acc[mi][1] = SWAP ? MFMA(br[ks & 1][1], ar[t % 3], acc[mi][1]) : MFMA(ar[t % 3], br[ks & 1][1], acc[mi][1]);
;         __builtin_amdgcn_sched_group_barrier(0x008, 2, 0);
;         if (SSQ) {
;           u32x4 u = __builtin_bit_cast(u32x4, ar[t % 3]);
; #pragma unroll
;           for (int j = 0; j < 4; ++j) rs[mi] = dot2bf(u[j], rs[mi]);
;         }
;       }
;     }
;     __syncthreads();
;     if (kt + 1 < nkt) sstore();
;     __syncthreads();
; DI void phase_inproj(const Params& p, const GroupP& g, int l, char* smem, int vb) {
;     ...
;     if (nw0 >= INW) continue;
;     if (l == 1) {
	ds_read_b128 v[138:141], v142 offset:36864
	ds_read_b128 v[154:157], v142 offset:41472
	ds_read_b128 v[144:147], v137
	ds_read_b128 v[150:153], v137 offset:4608
	ds_read_b128 v[158:161], v137 offset:9216
	s_or_b32 s65, s8, s55
	s_cmpk_gt_i32 s65, 0x153f
	s_waitcnt lgkmcnt(2)
	v_mfma_f32_32x32x16_bf16 v[112:127], v[138:141], v[144:147], v[112:127]
	v_mfma_f32_32x32x16_bf16 v[96:111], v[154:157], v[144:147], v[96:111]
	ds_read_b128 v[162:165], v142 offset:36896
	ds_read_b128 v[166:169], v142 offset:41504
	ds_read_b128 v[144:147], v137 offset:13824
	s_waitcnt lgkmcnt(4)
	v_mfma_f32_32x32x16_bf16 v[80:95], v[138:141], v[150:153], v[80:95]
	v_mfma_f32_32x32x16_bf16 v[64:79], v[154:157], v[150:153], v[64:79]
	ds_read_b128 v[150:153], v137 offset:32
	s_waitcnt lgkmcnt(4)
	v_mfma_f32_32x32x16_bf16 v[48:63], v[138:141], v[158:161], v[48:63]
	v_mfma_f32_32x32x16_bf16 v[32:47], v[154:157], v[158:161], v[32:47]
	ds_read_b128 v[158:161], v137 offset:4640
	s_waitcnt lgkmcnt(2)
	v_mfma_f32_32x32x16_bf16 v[16:31], v[138:141], v[144:147], v[16:31]
	v_mfma_f32_32x32x16_bf16 v[0:15], v[154:157], v[144:147], v[0:15]
	ds_read_b128 v[138:141], v137 offset:9248
	s_waitcnt lgkmcnt(2)
	v_mfma_f32_32x32x16_bf16 v[112:127], v[162:165], v[150:153], v[112:127]
	v_mfma_f32_32x32x16_bf16 v[96:111], v[166:169], v[150:153], v[96:111]
	ds_read_b128 v[150:153], v142 offset:36928
	ds_read_b128 v[154:157], v142 offset:41536
	ds_read_b128 v[144:147], v137 offset:13856
	s_waitcnt lgkmcnt(4)
	v_mfma_f32_32x32x16_bf16 v[80:95], v[162:165], v[158:161], v[80:95]
	v_mfma_f32_32x32x16_bf16 v[64:79], v[166:169], v[158:161], v[64:79]
	ds_read_b128 v[158:161], v137 offset:64
	s_waitcnt lgkmcnt(4)
	v_mfma_f32_32x32x16_bf16 v[48:63], v[162:165], v[138:141], v[48:63]
	v_mfma_f32_32x32x16_bf16 v[32:47], v[166:169], v[138:141], v[32:47]
	ds_read_b128 v[138:141], v137 offset:4672
	s_waitcnt lgkmcnt(2)
	v_mfma_f32_32x32x16_bf16 v[16:31], v[162:165], v[144:147], v[16:31]
	v_mfma_f32_32x32x16_bf16 v[0:15], v[166:169], v[144:147], v[0:15]
	ds_read_b128 v[144:147], v137 offset:9280
	s_waitcnt lgkmcnt(2)
	v_mfma_f32_32x32x16_bf16 v[112:127], v[150:153], v[158:161], v[112:127]
	v_mfma_f32_32x32x16_bf16 v[96:111], v[154:157], v[158:161], v[96:111]
	ds_read_b128 v[162:165], v142 offset:36960
	ds_read_b128 v[166:169], v142 offset:41568
	ds_read_b128 v[158:161], v137 offset:13888
	s_waitcnt lgkmcnt(4)
	v_mfma_f32_32x32x16_bf16 v[80:95], v[150:153], v[138:141], v[80:95]
	v_mfma_f32_32x32x16_bf16 v[64:79], v[154:157], v[138:141], v[64:79]
	ds_read_b128 v[138:141], v137 offset:96
	s_waitcnt lgkmcnt(4)
	v_mfma_f32_32x32x16_bf16 v[48:63], v[150:153], v[144:147], v[48:63]
	v_mfma_f32_32x32x16_bf16 v[32:47], v[154:157], v[144:147], v[32:47]
	ds_read_b128 v[142:145], v137 offset:4704
	s_waitcnt lgkmcnt(2)
	v_mfma_f32_32x32x16_bf16 v[16:31], v[150:153], v[158:161], v[16:31]
	v_mfma_f32_32x32x16_bf16 v[0:15], v[154:157], v[158:161], v[0:15]
	ds_read_b128 v[150:153], v137 offset:9312
	s_waitcnt lgkmcnt(2)
	v_mfma_f32_32x32x16_bf16 v[112:127], v[162:165], v[138:141], v[112:127]
	v_mfma_f32_32x32x16_bf16 v[96:111], v[166:169], v[138:141], v[96:111]
	ds_read_b128 v[136:139], v137 offset:13920
	s_waitcnt lgkmcnt(0)
	s_barrier
	s_nop 0
	v_mfma_f32_32x32x16_bf16 v[80:95], v[162:165], v[142:145], v[80:95]
	v_mfma_f32_32x32x16_bf16 v[64:79], v[166:169], v[142:145], v[64:79]
	v_mfma_f32_32x32x16_bf16 v[48:63], v[162:165], v[150:153], v[48:63]
	v_mfma_f32_32x32x16_bf16 v[32:47], v[166:169], v[150:153], v[32:47]
	v_mfma_f32_32x32x16_bf16 v[16:31], v[162:165], v[136:139], v[16:31]
	v_mfma_f32_32x32x16_bf16 v[0:15], v[166:169], v[136:139], v[0:15]
	s_cbranch_scc1 .LBB0_450
	v_readlane_b32 s12, v254, 31
	v_readlane_b32 s13, v254, 32
	s_andn2_b64 vcc, exec, s[12:13]
	s_cbranch_vccnz .LBB0_459
; DI void phase_inproj(const Params& p, const GroupP& g, int l, char* smem, int vb) {
;     ...
;     if (l == 1) {
;       const float* sq = p.rowsq + (size_t)4 * 50432 + g.seq0 + m0 + wm * 128 + lr;
; #pragma unroll
;       for (int mi = 0; mi < 4; ++mi) {
;         const float r = __builtin_amdgcn_rsqf(sq[mi * 32] * (1.f / DM) + 1e-6f);
; #pragma unroll
;         for (int ni = 0; ni < 2; ++ni)
; #pragma unroll
;           for (int i = 0; i < 16; ++i) acc[mi][ni][i] *= r;
;       }
;     }
	v_lshl_add_u64 v[136:137], s[10:11], 2, v[132:133]
	global_load_dword v138, v[136:137], off
	s_waitcnt vmcnt(0)
	v_fmamk_f32 v138, v138, 0x3a000000, v215
	v_rsq_f32_e32 v138, v138
	s_nop 0
	v_pk_mul_f32 v[126:127], v[126:127], v[138:139] op_sel_hi:[1,0]
	v_pk_mul_f32 v[124:125], v[124:125], v[138:139] op_sel_hi:[1,0]
	v_pk_mul_f32 v[122:123], v[122:123], v[138:139] op_sel_hi:[1,0]
	v_pk_mul_f32 v[120:121], v[120:121], v[138:139] op_sel_hi:[1,0]
	v_pk_mul_f32 v[118:119], v[118:119], v[138:139] op_sel_hi:[1,0]
	v_pk_mul_f32 v[116:117], v[116:117], v[138:139] op_sel_hi:[1,0]
	v_pk_mul_f32 v[114:115], v[114:115], v[138:139] op_sel_hi:[1,0]
	v_pk_mul_f32 v[112:113], v[112:113], v[138:139] op_sel_hi:[1,0]
	v_pk_mul_f32 v[110:111], v[110:111], v[138:139] op_sel_hi:[1,0]
	v_pk_mul_f32 v[108:109], v[108:109], v[138:139] op_sel_hi:[1,0]
	v_pk_mul_f32 v[106:107], v[106:107], v[138:139] op_sel_hi:[1,0]
	v_pk_mul_f32 v[104:105], v[104:105], v[138:139] op_sel_hi:[1,0]
	v_pk_mul_f32 v[102:103], v[102:103], v[138:139] op_sel_hi:[1,0]
	v_pk_mul_f32 v[100:101], v[100:101], v[138:139] op_sel_hi:[1,0]
	v_pk_mul_f32 v[98:99], v[98:99], v[138:139] op_sel_hi:[1,0]
	v_pk_mul_f32 v[96:97], v[96:97], v[138:139] op_sel_hi:[1,0]
	global_load_dword v138, v[136:137], off offset:128
	s_waitcnt vmcnt(0)
	v_fmamk_f32 v138, v138, 0x3a000000, v215
	v_rsq_f32_e32 v138, v138
	s_nop 0
	v_pk_mul_f32 v[94:95], v[94:95], v[138:139] op_sel_hi:[1,0]
	v_pk_mul_f32 v[92:93], v[92:93], v[138:139] op_sel_hi:[1,0]
	v_pk_mul_f32 v[90:91], v[90:91], v[138:139] op_sel_hi:[1,0]
	v_pk_mul_f32 v[88:89], v[88:89], v[138:139] op_sel_hi:[1,0]
	v_pk_mul_f32 v[86:87], v[86:87], v[138:139] op_sel_hi:[1,0]
	v_pk_mul_f32 v[84:85], v[84:85], v[138:139] op_sel_hi:[1,0]
	v_pk_mul_f32 v[82:83], v[82:83], v[138:139] op_sel_hi:[1,0]
	v_pk_mul_f32 v[80:81], v[80:81], v[138:139] op_sel_hi:[1,0]
	v_pk_mul_f32 v[78:79], v[78:79], v[138:139] op_sel_hi:[1,0]
	v_pk_mul_f32 v[76:77], v[76:77], v[138:139] op_sel_hi:[1,0]
	v_pk_mul_f32 v[74:75], v[74:75], v[138:139] op_sel_hi:[1,0]
	v_pk_mul_f32 v[72:73], v[72:73], v[138:139] op_sel_hi:[1,0]
	v_pk_mul_f32 v[70:71], v[70:71], v[138:139] op_sel_hi:[1,0]
	v_pk_mul_f32 v[68:69], v[68:69], v[138:139] op_sel_hi:[1,0]
	v_pk_mul_f32 v[66:67], v[66:67], v[138:139] op_sel_hi:[1,0]
	v_pk_mul_f32 v[64:65], v[64:65], v[138:139] op_sel_hi:[1,0]
	global_load_dword v138, v[136:137], off offset:256
	s_waitcnt vmcnt(0)
	v_fmamk_f32 v138, v138, 0x3a000000, v215
	global_load_dword v136, v[136:137], off offset:384
	v_rsq_f32_e32 v138, v138
	s_waitcnt vmcnt(0)
	v_fmamk_f32 v136, v136, 0x3a000000, v215
	v_rsq_f32_e32 v136, v136
	v_pk_mul_f32 v[62:63], v[62:63], v[138:139] op_sel_hi:[1,0]
	v_pk_mul_f32 v[60:61], v[60:61], v[138:139] op_sel_hi:[1,0]
	v_pk_mul_f32 v[58:59], v[58:59], v[138:139] op_sel_hi:[1,0]
	v_pk_mul_f32 v[56:57], v[56:57], v[138:139] op_sel_hi:[1,0]
	v_pk_mul_f32 v[54:55], v[54:55], v[138:139] op_sel_hi:[1,0]
	v_pk_mul_f32 v[52:53], v[52:53], v[138:139] op_sel_hi:[1,0]
	v_pk_mul_f32 v[50:51], v[50:51], v[138:139] op_sel_hi:[1,0]
	v_pk_mul_f32 v[48:49], v[48:49], v[138:139] op_sel_hi:[1,0]
	v_pk_mul_f32 v[46:47], v[46:47], v[138:139] op_sel_hi:[1,0]
	v_pk_mul_f32 v[44:45], v[44:45], v[138:139] op_sel_hi:[1,0]
	v_pk_mul_f32 v[42:43], v[42:43], v[138:139] op_sel_hi:[1,0]
	v_pk_mul_f32 v[40:41], v[40:41], v[138:139] op_sel_hi:[1,0]
	v_pk_mul_f32 v[38:39], v[38:39], v[138:139] op_sel_hi:[1,0]
	v_pk_mul_f32 v[36:37], v[36:37], v[138:139] op_sel_hi:[1,0]
	v_pk_mul_f32 v[34:35], v[34:35], v[138:139] op_sel_hi:[1,0]
	v_pk_mul_f32 v[32:33], v[32:33], v[138:139] op_sel_hi:[1,0]
	v_pk_mul_f32 v[30:31], v[30:31], v[136:137] op_sel_hi:[1,0]
	v_pk_mul_f32 v[28:29], v[28:29], v[136:137] op_sel_hi:[1,0]
	v_pk_mul_f32 v[26:27], v[26:27], v[136:137] op_sel_hi:[1,0]
	v_pk_mul_f32 v[24:25], v[24:25], v[136:137] op_sel_hi:[1,0]
	v_pk_mul_f32 v[22:23], v[22:23], v[136:137] op_sel_hi:[1,0]
	v_pk_mul_f32 v[20:21], v[20:21], v[136:137] op_sel_hi:[1,0]
	v_pk_mul_f32 v[18:19], v[18:19], v[136:137] op_sel_hi:[1,0]
	v_pk_mul_f32 v[16:17], v[16:17], v[136:137] op_sel_hi:[1,0]
	v_pk_mul_f32 v[14:15], v[14:15], v[136:137] op_sel_hi:[1,0]
	v_pk_mul_f32 v[12:13], v[12:13], v[136:137] op_sel_hi:[1,0]
	v_pk_mul_f32 v[10:11], v[10:11], v[136:137] op_sel_hi:[1,0]
	v_pk_mul_f32 v[8:9], v[8:9], v[136:137] op_sel_hi:[1,0]
	v_pk_mul_f32 v[6:7], v[6:7], v[136:137] op_sel_hi:[1,0]
	v_pk_mul_f32 v[4:5], v[4:5], v[136:137] op_sel_hi:[1,0]
	v_pk_mul_f32 v[2:3], v[2:3], v[136:137] op_sel_hi:[1,0]
	v_pk_mul_f32 v[0:1], v[0:1], v[136:137] op_sel_hi:[1,0]

; #define MFMA(a, b, c) __builtin_amdgcn_mfma_f32_32x32x16_bf16((a), (b), (c), 0, 0, 0)
; template <bool SWAP, bool SSQ, class AF>
; DI void gemm_main(AF asrc, int m0, const u16* __restrict__ Bw, int ldb, int K, char* smem,
;                   f32x16 (&acc)[4][2], float ssq_eps, float (&rs)[4]) {
;     ...
;   for (int kt = 0; kt < nkt; ++kt) {
;     if (kt + 1 < nkt) gload(kt + 1);
;     __builtin_amdgcn_sched_barrier(0);
;     {
;       bf16x8 ar[3], br[2][2];
;       ar[0] = *(const bf16x8*)(pA);
;       ar[1] = *(const bf16x8*)(pA + 32 * 144);
;       br[0][0] = *(const bf16x8*)(pB);
;       br[0][1] = *(const bf16x8*)(pB + 32 * 144);
;       __builtin_amdgcn_sched_group_barrier(0x100, 4, 0);
; #pragma unroll
;       for (int t = 0; t < 16; ++t) {
;         const int ks = t >> 2, mi = t & 3;
;         if (t + 2 < 16) {
;           ar[(t + 2) % 3] = *(const bf16x8*)(pA + ((t + 2) & 3) * (32 * 144) + ((t + 2) >> 2) * 32);
;           if (mi == 1 && ks + 1 < 4) {
;             br[(ks + 1) & 1][0] = *(const bf16x8*)(pB + (ks + 1) * 32);
;             br[(ks + 1) & 1][1] = *(const bf16x8*)(pB + 32 * 144 + (ks + 1) * 32);
;             __builtin_amdgcn_sched_group_barrier(0x100, 3, 0);
;           } else {
;             __builtin_amdgcn_sched_group_barrier(0x100, 1, 0);
;           }
;         }
;         acc[mi][0] = SWAP ? MFMA(br[ks & 1][0], ar[t % 3], acc[mi][0]) : MFMA(ar[t % 3], br[ks & 1][0], acc[mi][0]);
;         acc[mi][1] = SWAP ? MFMA(br[ks & 1][1], ar[t % 3], acc[mi][1]) : MFMA(ar[t % 3], br[ks & 1][1], acc[mi][1]);
;         __builtin_amdgcn_sched_group_barrier(0x008, 2, 0);
;         if (SSQ) {
;           u32x4 u = __builtin_bit_cast(u32x4, ar[t % 3]);
; #pragma unroll
;           for (int j = 0; j < 4; ++j) rs[mi] = dot2bf(u[j], rs[mi]);
;         }
;       }
;     }
;     __syncthreads();
;     if (kt + 1 < nkt) sstore();
;     __syncthreads();
;   }
.LBB0_588:
	ds_read_b128 v[238:241], v137 offset:13824
	global_load_dwordx4 v[144:147], v198, s[34:35]
	global_load_dwordx4 v[150:153], v199, s[34:35]
	s_waitcnt lgkmcnt(3)
	v_mfma_f32_32x32x16_bf16 v[112:127], v[218:221], v[226:229], v[112:127]
	v_mfma_f32_32x32x16_bf16 v[96:111], v[222:225], v[226:229], v[96:111]
	ds_read_b128 v[226:229], v142 offset:36896
	ds_read_b128 v[242:245], v142 offset:41504
	global_load_dwordx4 v[154:157], v217, s[34:35]
	global_load_dwordx4 v[158:161], v250, s[34:35]
	s_waitcnt lgkmcnt(4)
	v_mfma_f32_32x32x16_bf16 v[80:95], v[218:221], v[230:233], v[80:95]
	v_mfma_f32_32x32x16_bf16 v[64:79], v[222:225], v[230:233], v[64:79]
	ds_read_b128 v[230:233], v137 offset:32
	global_load_dwordx4 v[162:165], v198, s[36:37]
	global_load_dwordx4 v[166:169], v199, s[36:37]
	s_waitcnt lgkmcnt(4)
	v_mfma_f32_32x32x16_bf16 v[48:63], v[218:221], v[234:237], v[48:63]
	v_mfma_f32_32x32x16_bf16 v[32:47], v[222:225], v[234:237], v[32:47]
	ds_read_b128 v[234:237], v137 offset:4640
	global_load_dwordx4 v[170:173], v217, s[36:37]
	global_load_dwordx4 v[174:177], v250, s[36:37]
	s_waitcnt lgkmcnt(4)
	v_mfma_f32_32x32x16_bf16 v[16:31], v[218:221], v[238:241], v[16:31]
	v_mfma_f32_32x32x16_bf16 v[0:15], v[222:225], v[238:241], v[0:15]
	ds_read_b128 v[218:221], v137 offset:9248
	ds_read_b128 v[222:225], v137 offset:13856
	global_load_dwordx4 v[178:181], v198, s[100:101]
	global_load_dwordx4 v[186:189], v199, s[100:101]
	s_waitcnt lgkmcnt(3)
	v_mfma_f32_32x32x16_bf16 v[112:127], v[226:229], v[230:233], v[112:127]
	v_mfma_f32_32x32x16_bf16 v[96:111], v[242:245], v[230:233], v[96:111]
	ds_read_b128 v[230:233], v142 offset:36928
	ds_read_b128 v[202:205], v142 offset:41536
	global_load_dwordx4 v[190:193], v217, s[100:101]
	global_load_dwordx4 v[194:197], v250, s[100:101]
	s_waitcnt lgkmcnt(4)
	v_mfma_f32_32x32x16_bf16 v[80:95], v[226:229], v[234:237], v[80:95]
	v_mfma_f32_32x32x16_bf16 v[64:79], v[242:245], v[234:237], v[64:79]
	ds_read_b128 v[234:237], v137 offset:64
	ds_read_b128 v[206:209], v137 offset:4672
	s_waitcnt lgkmcnt(5)
	v_mfma_f32_32x32x16_bf16 v[48:63], v[226:229], v[218:221], v[48:63]
	v_mfma_f32_32x32x16_bf16 v[32:47], v[242:245], v[218:221], v[32:47]
	ds_read_b128 v[218:221], v137 offset:9280
	s_waitcnt lgkmcnt(5)
	v_mfma_f32_32x32x16_bf16 v[16:31], v[226:229], v[222:225], v[16:31]
	v_mfma_f32_32x32x16_bf16 v[0:15], v[242:245], v[222:225], v[0:15]
	ds_read_b128 v[226:229], v137 offset:13888
	ds_read_b128 v[246:249], v142 offset:36960
	ds_read_b128 v[238:241], v142 offset:41568
	s_waitcnt lgkmcnt(5)
	v_mfma_f32_32x32x16_bf16 v[112:127], v[230:233], v[234:237], v[112:127]
	v_mfma_f32_32x32x16_bf16 v[96:111], v[202:205], v[234:237], v[96:111]
	ds_read_b128 v[222:225], v137 offset:96
	ds_read_b128 v[234:237], v137 offset:4704
	s_waitcnt lgkmcnt(6)
	v_mfma_f32_32x32x16_bf16 v[80:95], v[230:233], v[206:209], v[80:95]
	v_mfma_f32_32x32x16_bf16 v[64:79], v[202:205], v[206:209], v[64:79]
	ds_read_b128 v[242:245], v137 offset:9312
	ds_read_b128 v[206:209], v137 offset:13920
	s_waitcnt lgkmcnt(0)
	s_barrier
	v_mfma_f32_32x32x16_bf16 v[48:63], v[230:233], v[218:221], v[48:63]
	v_mfma_f32_32x32x16_bf16 v[32:47], v[202:205], v[218:221], v[32:47]
	s_waitcnt vmcnt(11)
	ds_write_b128 v136, v[144:147]
	s_waitcnt vmcnt(10)
	ds_write_b128 v136, v[150:153] offset:4608
	s_waitcnt vmcnt(9)
	ds_write_b128 v136, v[154:157] offset:9216
	s_waitcnt vmcnt(8)
	ds_write_b128 v136, v[158:161] offset:13824
	v_mfma_f32_32x32x16_bf16 v[16:31], v[230:233], v[226:229], v[16:31]
	v_mfma_f32_32x32x16_bf16 v[0:15], v[202:205], v[226:229], v[0:15]
	s_waitcnt vmcnt(7)
	ds_write_b128 v136, v[162:165] offset:18432
	s_waitcnt vmcnt(6)
	ds_write_b128 v136, v[166:169] offset:23040
	s_waitcnt vmcnt(5)
	ds_write_b128 v136, v[170:173] offset:27648
	s_waitcnt vmcnt(4)
	ds_write_b128 v136, v[174:177] offset:32256
	v_mfma_f32_32x32x16_bf16 v[112:127], v[246:249], v[222:225], v[112:127]
	v_mfma_f32_32x32x16_bf16 v[96:111], v[238:241], v[222:225], v[96:111]
	s_waitcnt vmcnt(3)
	ds_write_b128 v136, v[178:181] offset:36864
	s_waitcnt vmcnt(2)
	ds_write_b128 v136, v[186:189] offset:41472
	s_waitcnt vmcnt(1)
	ds_write_b128 v136, v[190:193] offset:46080
	s_waitcnt vmcnt(0)
	ds_write_b128 v136, v[194:197] offset:50688
	v_mfma_f32_32x32x16_bf16 v[80:95], v[246:249], v[234:237], v[80:95]
	v_mfma_f32_32x32x16_bf16 v[64:79], v[238:241], v[234:237], v[64:79]
	s_waitcnt lgkmcnt(0)
	s_barrier
	ds_read_b128 v[218:221], v142 offset:36864
	ds_read_b128 v[222:225], v142 offset:41472
	ds_read_b128 v[226:229], v137
	ds_read_b128 v[230:233], v137 offset:4608
	ds_read_b128 v[234:237], v137 offset:9216
	v_mfma_f32_32x32x16_bf16 v[48:63], v[246:249], v[242:245], v[48:63]
	v_mfma_f32_32x32x16_bf16 v[32:47], v[238:241], v[242:245], v[32:47]
	v_mfma_f32_32x32x16_bf16 v[16:31], v[246:249], v[206:209], v[16:31]
	v_mfma_f32_32x32x16_bf16 v[0:15], v[238:241], v[206:209], v[0:15]
	s_add_u32 s34, s34, 0x80
	s_addc_u32 s35, s35, 0
	s_add_u32 s36, s36, 0x80
	s_addc_u32 s37, s37, 0
	s_add_u32 s100, s100, 0x80
	s_addc_u32 s101, s101, 0
	s_add_u32 s12, s12, 0x80
	s_cmpk_lg_i32 s12, 0xf80
	s_cbranch_scc1 .LBB0_588
; #define MFMA(a, b, c) __builtin_amdgcn_mfma_f32_32x32x16_bf16((a), (b), (c), 0, 0, 0)
; template <bool SWAP, bool SSQ, class AF>
; DI void gemm_main(AF asrc, int m0, const u16* __restrict__ Bw, int ldb, int K, char* smem,
;                   f32x16 (&acc)[4][2], float ssq_eps, float (&rs)[4]) {
;     ...
;     {
;       bf16x8 ar[3], br[2][2];
;       ar[0] = *(const bf16x8*)(pA);
;       ar[1] = *(const bf16x8*)(pA + 32 * 144);
;       br[0][0] = *(const bf16x8*)(pB);
;       br[0][1] = *(const bf16x8*)(pB + 32 * 144);
;       __builtin_amdgcn_sched_group_barrier(0x100, 4, 0);
; #pragma unroll
;       for (int t = 0; t < 16; ++t) {
;         const int ks = t >> 2, mi = t & 3;
;         if (t + 2 < 16) {
;           ar[(t + 2) % 3] = *(const bf16x8*)(pA + ((t + 2) & 3) * (32 * 144) + ((t + 2) >> 2) * 32);
;           if (mi == 1 && ks + 1 < 4) {
;             br[(ks + 1) & 1][0] = *(const bf16x8*)(pB + (ks + 1) * 32);
;             br[(ks + 1) & 1][1] = *(const bf16x8*)(pB + 32 * 144 + (ks + 1) * 32);
;             __builtin_amdgcn_sched_group_barrier(0x100, 3, 0);
;           } else {
;             __builtin_amdgcn_sched_group_barrier(0x100, 1, 0);
;           }
;         }
;         acc[mi][0] = SWAP ? MFMA(br[ks & 1][0], ar[t % 3], acc[mi][0]) : MFMA(ar[t % 3], br[ks & 1][0], acc[mi][0]);
;         acc[mi][1] = SWAP ? MFMA(br[ks & 1][1], ar[t % 3], acc[mi][1]) : MFMA(ar[t % 3], br[ks & 1][1], acc[mi][1]);
;         __builtin_amdgcn_sched_group_barrier(0x008, 2, 0);
;         if (SSQ) {
;           u32x4 u = __builtin_bit_cast(u32x4, ar[t % 3]);
; #pragma unroll
;           for (int j = 0; j < 4; ++j) rs[mi] = dot2bf(u[j], rs[mi]);
;         }
;       }
;     }
;     __syncthreads();
;     if (kt + 1 < nkt) sstore();
;     __syncthreads();
; DI void phase_inproj(const Params& p, const GroupP& g, int l, char* smem, int vb) {
;     ...
;     if (nw0 >= INW) continue;
;     if (l == 1) {
	ds_read_b128 v[138:141], v142 offset:36864
	ds_read_b128 v[154:157], v142 offset:41472
	ds_read_b128 v[144:147], v137
	ds_read_b128 v[150:153], v137 offset:4608
	ds_read_b128 v[158:161], v137 offset:9216
	s_or_b32 s64, s8, s56
	s_cmpk_gt_i32 s64, 0x153f
	s_waitcnt lgkmcnt(2)
	v_mfma_f32_32x32x16_bf16 v[112:127], v[138:141], v[144:147], v[112:127]
	v_mfma_f32_32x32x16_bf16 v[96:111], v[154:157], v[144:147], v[96:111]
	ds_read_b128 v[162:165], v142 offset:36896
	ds_read_b128 v[166:169], v142 offset:41504
	ds_read_b128 v[144:147], v137 offset:13824
	s_waitcnt lgkmcnt(4)
	v_mfma_f32_32x32x16_bf16 v[80:95], v[138:141], v[150:153], v[80:95]
	v_mfma_f32_32x32x16_bf16 v[64:79], v[154:157], v[150:153], v[64:79]
	ds_read_b128 v[150:153], v137 offset:32
	s_waitcnt lgkmcnt(4)
	v_mfma_f32_32x32x16_bf16 v[48:63], v[138:141], v[158:161], v[48:63]
	v_mfma_f32_32x32x16_bf16 v[32:47], v[154:157], v[158:161], v[32:47]
	ds_read_b128 v[158:161], v137 offset:4640
	s_waitcnt lgkmcnt(2)
	v_mfma_f32_32x32x16_bf16 v[16:31], v[138:141], v[144:147], v[16:31]
	v_mfma_f32_32x32x16_bf16 v[0:15], v[154:157], v[144:147], v[0:15]
	ds_read_b128 v[138:141], v137 offset:9248
	s_waitcnt lgkmcnt(2)
	v_mfma_f32_32x32x16_bf16 v[112:127], v[162:165], v[150:153], v[112:127]
	v_mfma_f32_32x32x16_bf16 v[96:111], v[166:169], v[150:153], v[96:111]
	ds_read_b128 v[150:153], v142 offset:36928
	ds_read_b128 v[154:157], v142 offset:41536
	ds_read_b128 v[144:147], v137 offset:13856
	s_waitcnt lgkmcnt(4)
	v_mfma_f32_32x32x16_bf16 v[80:95], v[162:165], v[158:161], v[80:95]
	v_mfma_f32_32x32x16_bf16 v[64:79], v[166:169], v[158:161], v[64:79]
	ds_read_b128 v[158:161], v137 offset:64
	s_waitcnt lgkmcnt(4)
	v_mfma_f32_32x32x16_bf16 v[48:63], v[162:165], v[138:141], v[48:63]
	v_mfma_f32_32x32x16_bf16 v[32:47], v[166:169], v[138:141], v[32:47]
	ds_read_b128 v[138:141], v137 offset:4672
	s_waitcnt lgkmcnt(2)
	v_mfma_f32_32x32x16_bf16 v[16:31], v[162:165], v[144:147], v[16:31]
	v_mfma_f32_32x32x16_bf16 v[0:15], v[166:169], v[144:147], v[0:15]
	ds_read_b128 v[144:147], v137 offset:9280
	s_waitcnt lgkmcnt(2)
	v_mfma_f32_32x32x16_bf16 v[112:127], v[150:153], v[158:161], v[112:127]
	v_mfma_f32_32x32x16_bf16 v[96:111], v[154:157], v[158:161], v[96:111]
	ds_read_b128 v[162:165], v142 offset:36960
	ds_read_b128 v[166:169], v142 offset:41568
	ds_read_b128 v[158:161], v137 offset:13888
	s_waitcnt lgkmcnt(4)
	v_mfma_f32_32x32x16_bf16 v[80:95], v[150:153], v[138:141], v[80:95]
	v_mfma_f32_32x32x16_bf16 v[64:79], v[154:157], v[138:141], v[64:79]
	ds_read_b128 v[138:141], v137 offset:96
	s_waitcnt lgkmcnt(4)
	v_mfma_f32_32x32x16_bf16 v[48:63], v[150:153], v[144:147], v[48:63]
	v_mfma_f32_32x32x16_bf16 v[32:47], v[154:157], v[144:147], v[32:47]
	ds_read_b128 v[142:145], v137 offset:4704
	s_waitcnt lgkmcnt(2)
	v_mfma_f32_32x32x16_bf16 v[16:31], v[150:153], v[158:161], v[16:31]
	v_mfma_f32_32x32x16_bf16 v[0:15], v[154:157], v[158:161], v[0:15]
	ds_read_b128 v[150:153], v137 offset:9312
	s_waitcnt lgkmcnt(2)
	v_mfma_f32_32x32x16_bf16 v[112:127], v[162:165], v[138:141], v[112:127]
	v_mfma_f32_32x32x16_bf16 v[96:111], v[166:169], v[138:141], v[96:111]
	ds_read_b128 v[136:139], v137 offset:13920
	s_waitcnt lgkmcnt(0)
	s_barrier
	s_nop 0
	v_mfma_f32_32x32x16_bf16 v[80:95], v[162:165], v[142:145], v[80:95]
	v_mfma_f32_32x32x16_bf16 v[64:79], v[166:169], v[142:145], v[64:79]
	v_mfma_f32_32x32x16_bf16 v[48:63], v[162:165], v[150:153], v[48:63]
	v_mfma_f32_32x32x16_bf16 v[32:47], v[166:169], v[150:153], v[32:47]
	v_mfma_f32_32x32x16_bf16 v[16:31], v[162:165], v[136:139], v[16:31]
	v_mfma_f32_32x32x16_bf16 v[0:15], v[166:169], v[136:139], v[0:15]
	s_cbranch_scc1 .LBB0_583
	v_readlane_b32 s12, v254, 31
	v_readlane_b32 s13, v254, 32
	s_andn2_b64 vcc, exec, s[12:13]
	s_cbranch_vccnz .LBB0_592
; DI void phase_inproj(const Params& p, const GroupP& g, int l, char* smem, int vb) {
;     ...
;     if (l == 1) {
;       const float* sq = p.rowsq + (size_t)4 * 50432 + g.seq0 + m0 + wm * 128 + lr;
; #pragma unroll
;       for (int mi = 0; mi < 4; ++mi) {
;         const float r = __builtin_amdgcn_rsqf(sq[mi * 32] * (1.f / DM) + 1e-6f);
; #pragma unroll
;         for (int ni = 0; ni < 2; ++ni)
; #pragma unroll
;           for (int i = 0; i < 16; ++i) acc[mi][ni][i] *= r;
;       }
;     }
	v_lshl_add_u64 v[136:137], s[10:11], 2, v[132:133]
	global_load_dword v138, v[136:137], off
	s_waitcnt vmcnt(0)
	v_fmamk_f32 v138, v138, 0x3a000000, v215
	v_rsq_f32_e32 v138, v138
	s_nop 0
	v_pk_mul_f32 v[126:127], v[126:127], v[138:139] op_sel_hi:[1,0]
	v_pk_mul_f32 v[124:125], v[124:125], v[138:139] op_sel_hi:[1,0]
	v_pk_mul_f32 v[122:123], v[122:123], v[138:139] op_sel_hi:[1,0]
	v_pk_mul_f32 v[120:121], v[120:121], v[138:139] op_sel_hi:[1,0]
	v_pk_mul_f32 v[118:119], v[118:119], v[138:139] op_sel_hi:[1,0]
	v_pk_mul_f32 v[116:117], v[116:117], v[138:139] op_sel_hi:[1,0]
	v_pk_mul_f32 v[114:115], v[114:115], v[138:139] op_sel_hi:[1,0]
	v_pk_mul_f32 v[112:113], v[112:113], v[138:139] op_sel_hi:[1,0]
	v_pk_mul_f32 v[110:111], v[110:111], v[138:139] op_sel_hi:[1,0]
	v_pk_mul_f32 v[108:109], v[108:109], v[138:139] op_sel_hi:[1,0]
	v_pk_mul_f32 v[106:107], v[106:107], v[138:139] op_sel_hi:[1,0]
	v_pk_mul_f32 v[104:105], v[104:105], v[138:139] op_sel_hi:[1,0]
	v_pk_mul_f32 v[102:103], v[102:103], v[138:139] op_sel_hi:[1,0]
	v_pk_mul_f32 v[100:101], v[100:101], v[138:139] op_sel_hi:[1,0]
	v_pk_mul_f32 v[98:99], v[98:99], v[138:139] op_sel_hi:[1,0]
	v_pk_mul_f32 v[96:97], v[96:97], v[138:139] op_sel_hi:[1,0]
	global_load_dword v138, v[136:137], off offset:128
	s_waitcnt vmcnt(0)
	v_fmamk_f32 v138, v138, 0x3a000000, v215
	v_rsq_f32_e32 v138, v138
	s_nop 0
	v_pk_mul_f32 v[94:95], v[94:95], v[138:139] op_sel_hi:[1,0]
	v_pk_mul_f32 v[92:93], v[92:93], v[138:139] op_sel_hi:[1,0]
	v_pk_mul_f32 v[90:91], v[90:91], v[138:139] op_sel_hi:[1,0]
	v_pk_mul_f32 v[88:89], v[88:89], v[138:139] op_sel_hi:[1,0]
	v_pk_mul_f32 v[86:87], v[86:87], v[138:139] op_sel_hi:[1,0]
	v_pk_mul_f32 v[84:85], v[84:85], v[138:139] op_sel_hi:[1,0]
	v_pk_mul_f32 v[82:83], v[82:83], v[138:139] op_sel_hi:[1,0]
	v_pk_mul_f32 v[80:81], v[80:81], v[138:139] op_sel_hi:[1,0]
	v_pk_mul_f32 v[78:79], v[78:79], v[138:139] op_sel_hi:[1,0]
	v_pk_mul_f32 v[76:77], v[76:77], v[138:139] op_sel_hi:[1,0]
	v_pk_mul_f32 v[74:75], v[74:75], v[138:139] op_sel_hi:[1,0]
	v_pk_mul_f32 v[72:73], v[72:73], v[138:139] op_sel_hi:[1,0]
	v_pk_mul_f32 v[70:71], v[70:71], v[138:139] op_sel_hi:[1,0]
	v_pk_mul_f32 v[68:69], v[68:69], v[138:139] op_sel_hi:[1,0]
	v_pk_mul_f32 v[66:67], v[66:67], v[138:139] op_sel_hi:[1,0]
	v_pk_mul_f32 v[64:65], v[64:65], v[138:139] op_sel_hi:[1,0]
	global_load_dword v138, v[136:137], off offset:256
	s_waitcnt vmcnt(0)
	v_fmamk_f32 v138, v138, 0x3a000000, v215
	global_load_dword v136, v[136:137], off offset:384
	v_rsq_f32_e32 v138, v138
	s_waitcnt vmcnt(0)
	v_fmamk_f32 v136, v136, 0x3a000000, v215
	v_rsq_f32_e32 v136, v136
	v_pk_mul_f32 v[62:63], v[62:63], v[138:139] op_sel_hi:[1,0]
	v_pk_mul_f32 v[60:61], v[60:61], v[138:139] op_sel_hi:[1,0]
	v_pk_mul_f32 v[58:59], v[58:59], v[138:139] op_sel_hi:[1,0]
	v_pk_mul_f32 v[56:57], v[56:57], v[138:139] op_sel_hi:[1,0]
	v_pk_mul_f32 v[54:55], v[54:55], v[138:139] op_sel_hi:[1,0]
	v_pk_mul_f32 v[52:53], v[52:53], v[138:139] op_sel_hi:[1,0]
	v_pk_mul_f32 v[50:51], v[50:51], v[138:139] op_sel_hi:[1,0]
	v_pk_mul_f32 v[48:49], v[48:49], v[138:139] op_sel_hi:[1,0]
	v_pk_mul_f32 v[46:47], v[46:47], v[138:139] op_sel_hi:[1,0]
	v_pk_mul_f32 v[44:45], v[44:45], v[138:139] op_sel_hi:[1,0]
	v_pk_mul_f32 v[42:43], v[42:43], v[138:139] op_sel_hi:[1,0]
	v_pk_mul_f32 v[40:41], v[40:41], v[138:139] op_sel_hi:[1,0]
	v_pk_mul_f32 v[38:39], v[38:39], v[138:139] op_sel_hi:[1,0]
	v_pk_mul_f32 v[36:37], v[36:37], v[138:139] op_sel_hi:[1,0]
	v_pk_mul_f32 v[34:35], v[34:35], v[138:139] op_sel_hi:[1,0]
	v_pk_mul_f32 v[32:33], v[32:33], v[138:139] op_sel_hi:[1,0]
	v_pk_mul_f32 v[30:31], v[30:31], v[136:137] op_sel_hi:[1,0]
	v_pk_mul_f32 v[28:29], v[28:29], v[136:137] op_sel_hi:[1,0]
	v_pk_mul_f32 v[26:27], v[26:27], v[136:137] op_sel_hi:[1,0]
	v_pk_mul_f32 v[24:25], v[24:25], v[136:137] op_sel_hi:[1,0]
	v_pk_mul_f32 v[22:23], v[22:23], v[136:137] op_sel_hi:[1,0]
	v_pk_mul_f32 v[20:21], v[20:21], v[136:137] op_sel_hi:[1,0]
	v_pk_mul_f32 v[18:19], v[18:19], v[136:137] op_sel_hi:[1,0]
	v_pk_mul_f32 v[16:17], v[16:17], v[136:137] op_sel_hi:[1,0]
	v_pk_mul_f32 v[14:15], v[14:15], v[136:137] op_sel_hi:[1,0]
	v_pk_mul_f32 v[12:13], v[12:13], v[136:137] op_sel_hi:[1,0]
	v_pk_mul_f32 v[10:11], v[10:11], v[136:137] op_sel_hi:[1,0]
	v_pk_mul_f32 v[8:9], v[8:9], v[136:137] op_sel_hi:[1,0]
	v_pk_mul_f32 v[6:7], v[6:7], v[136:137] op_sel_hi:[1,0]
	v_pk_mul_f32 v[4:5], v[4:5], v[136:137] op_sel_hi:[1,0]
	v_pk_mul_f32 v[2:3], v[2:3], v[136:137] op_sel_hi:[1,0]
	v_pk_mul_f32 v[0:1], v[0:1], v[136:137] op_sel_hi:[1,0]

; #define MFMA(a, b, c) __builtin_amdgcn_mfma_f32_32x32x16_bf16((a), (b), (c), 0, 0, 0)
; template <bool SWAP, bool SSQ, class AF>
; DI void gemm_main(AF asrc, int m0, const u16* __restrict__ Bw, int ldb, int K, char* smem,
;                   f32x16 (&acc)[4][2], float ssq_eps, float (&rs)[4]) {
;     ...
;     {
;       bf16x8 ar[3], br[2][2];
;       ar[0] = *(const bf16x8*)(pA);
;       ar[1] = *(const bf16x8*)(pA + 32 * 144);
;       br[0][0] = *(const bf16x8*)(pB);
;       br[0][1] = *(const bf16x8*)(pB + 32 * 144);
;       __builtin_amdgcn_sched_group_barrier(0x100, 4, 0);
; #pragma unroll
;       for (int t = 0; t < 16; ++t) {
;         const int ks = t >> 2, mi = t & 3;
;         if (t + 2 < 16) {
;           ar[(t + 2) % 3] = *(const bf16x8*)(pA + ((t + 2) & 3) * (32 * 144) + ((t + 2) >> 2) * 32);
;           if (mi == 1 && ks + 1 < 4) {
;             br[(ks + 1) & 1][0] = *(const bf16x8*)(pB + (ks + 1) * 32);
;             br[(ks + 1) & 1][1] = *(const bf16x8*)(pB + 32 * 144 + (ks + 1) * 32);
;             __builtin_amdgcn_sched_group_barrier(0x100, 3, 0);
;           } else {
;             __builtin_amdgcn_sched_group_barrier(0x100, 1, 0);
;           }
;         }
;         acc[mi][0] = SWAP ? MFMA(br[ks & 1][0], ar[t % 3], acc[mi][0]) : MFMA(ar[t % 3], br[ks & 1][0], acc[mi][0]);
;         acc[mi][1] = SWAP ? MFMA(br[ks & 1][1], ar[t % 3], acc[mi][1]) : MFMA(ar[t % 3], br[ks & 1][1], acc[mi][1]);
;         __builtin_amdgcn_sched_group_barrier(0x008, 2, 0);
;         if (SSQ) {
;           u32x4 u = __builtin_bit_cast(u32x4, ar[t % 3]);
; #pragma unroll
;           for (int j = 0; j < 4; ++j) rs[mi] = dot2bf(u[j], rs[mi]);
;         }
;       }
;     }
;     __syncthreads();
;     if (kt + 1 < nkt) sstore();
;     __syncthreads();
; DI void phase_outproj(const Params& p, const GroupP& g, int l, char* smem, int vb) {
;     ...
;     for (int mi = 0; mi < 4; ++mi) {
;       int m = m0 + wm * 128 + mi * 32 + lr;
;       int b = m / g.Lp, t = m - b * g.Lp;
;       if (t >= g.L) continue;
;       if (l == 0) {
;         const float* res = (t < 16) ? p.meta + t * DM : g.x + ((long)b * (g.L - 16) + (t - 16)) * DM;
;         u16* dst = g.h1b + (long)m * DM;
.LBB0_916:
	ds_read_b128 v[140:143], v135 offset:36864
	ds_read_b128 v[152:155], v135 offset:41472
	ds_read_b128 v[144:147], v133
	ds_read_b128 v[148:151], v133 offset:4608
	ds_read_b128 v[156:159], v133 offset:9216
	v_add_u32_e32 v132, s8, v129
	s_or_b32 s8, s6, s31
	s_waitcnt lgkmcnt(2)
	v_mfma_f32_32x32x16_bf16 v[112:127], v[140:143], v[144:147], v[112:127]
	v_mfma_f32_32x32x16_bf16 v[96:111], v[152:155], v[144:147], v[96:111]
	ds_read_b128 v[160:163], v135 offset:36896
	ds_read_b128 v[164:167], v135 offset:41504
	ds_read_b128 v[144:147], v133 offset:13824
	s_waitcnt lgkmcnt(4)
	v_mfma_f32_32x32x16_bf16 v[80:95], v[140:143], v[148:151], v[80:95]
	v_mfma_f32_32x32x16_bf16 v[64:79], v[152:155], v[148:151], v[64:79]
	ds_read_b128 v[148:151], v133 offset:32
	s_waitcnt lgkmcnt(4)
	v_mfma_f32_32x32x16_bf16 v[48:63], v[140:143], v[156:159], v[48:63]
	v_mfma_f32_32x32x16_bf16 v[32:47], v[152:155], v[156:159], v[32:47]
	ds_read_b128 v[156:159], v133 offset:4640
	s_waitcnt lgkmcnt(2)
	v_mfma_f32_32x32x16_bf16 v[0:15], v[152:155], v[144:147], v[0:15]
	v_mfma_f32_32x32x16_bf16 v[16:31], v[140:143], v[144:147], v[16:31]
	ds_read_b128 v[140:143], v133 offset:9248
	s_waitcnt lgkmcnt(2)
	v_mfma_f32_32x32x16_bf16 v[112:127], v[160:163], v[148:151], v[112:127]
	v_mfma_f32_32x32x16_bf16 v[96:111], v[164:167], v[148:151], v[96:111]
	ds_read_b128 v[148:151], v135 offset:36928
	ds_read_b128 v[152:155], v135 offset:41536
	ds_read_b128 v[144:147], v133 offset:13856
	s_waitcnt lgkmcnt(4)
	v_mfma_f32_32x32x16_bf16 v[80:95], v[160:163], v[156:159], v[80:95]
	v_mfma_f32_32x32x16_bf16 v[64:79], v[164:167], v[156:159], v[64:79]
	ds_read_b128 v[156:159], v133 offset:64
	s_waitcnt lgkmcnt(4)
	v_mfma_f32_32x32x16_bf16 v[48:63], v[160:163], v[140:143], v[48:63]
	v_mfma_f32_32x32x16_bf16 v[32:47], v[164:167], v[140:143], v[32:47]
	ds_read_b128 v[140:143], v133 offset:4672
	s_waitcnt lgkmcnt(2)
	v_mfma_f32_32x32x16_bf16 v[0:15], v[164:167], v[144:147], v[0:15]
	v_mfma_f32_32x32x16_bf16 v[16:31], v[160:163], v[144:147], v[16:31]
	ds_read_b128 v[144:147], v133 offset:9280
	s_waitcnt lgkmcnt(2)
	v_mfma_f32_32x32x16_bf16 v[112:127], v[148:151], v[156:159], v[112:127]
	v_mfma_f32_32x32x16_bf16 v[96:111], v[152:155], v[156:159], v[96:111]
	ds_read_b128 v[160:163], v135 offset:36960
	ds_read_b128 v[134:137], v135 offset:41568
	ds_read_b128 v[156:159], v133 offset:13888
	s_waitcnt lgkmcnt(4)
	v_mfma_f32_32x32x16_bf16 v[80:95], v[148:151], v[140:143], v[80:95]
	v_mfma_f32_32x32x16_bf16 v[64:79], v[152:155], v[140:143], v[64:79]
	ds_read_b128 v[140:143], v133 offset:96
	s_waitcnt lgkmcnt(4)
	v_mfma_f32_32x32x16_bf16 v[48:63], v[148:151], v[144:147], v[48:63]
	v_mfma_f32_32x32x16_bf16 v[32:47], v[152:155], v[144:147], v[32:47]
	ds_read_b128 v[144:147], v133 offset:4704
	s_waitcnt lgkmcnt(2)
	v_mfma_f32_32x32x16_bf16 v[0:15], v[152:155], v[156:159], v[0:15]
	v_mfma_f32_32x32x16_bf16 v[16:31], v[148:151], v[156:159], v[16:31]
	ds_read_b128 v[148:151], v133 offset:9312
	s_waitcnt lgkmcnt(2)
	v_mfma_f32_32x32x16_bf16 v[112:127], v[160:163], v[140:143], v[112:127]
	v_mfma_f32_32x32x16_bf16 v[96:111], v[134:137], v[140:143], v[96:111]
	ds_read_b128 v[140:143], v133 offset:13920
	v_ashrrev_i32_e32 v133, 31, v132
	s_waitcnt lgkmcnt(0)
	s_barrier
	s_nop 0
	v_mfma_f32_32x32x16_bf16 v[80:95], v[160:163], v[144:147], v[80:95]
	v_mfma_f32_32x32x16_bf16 v[64:79], v[134:137], v[144:147], v[64:79]
	v_mfma_f32_32x32x16_bf16 v[48:63], v[160:163], v[148:151], v[48:63]
	v_mfma_f32_32x32x16_bf16 v[32:47], v[134:137], v[148:151], v[32:47]
	v_mfma_f32_32x32x16_bf16 v[0:15], v[134:137], v[140:143], v[0:15]
	v_sub_u32_e32 v134, 0, v132
	v_max_i32_e32 v134, v132, v134
	v_mul_hi_u32 v135, v134, v138
	v_mul_lo_u32 v137, v135, s35
	v_sub_u32_e32 v134, v134, v137
	v_cmp_le_u32_e32 vcc, s35, v134
	v_add_u32_e32 v137, 1, v135
	v_mfma_f32_32x32x16_bf16 v[16:31], v[160:163], v[140:143], v[16:31]
	v_cndmask_b32_e32 v135, v135, v137, vcc
	v_subrev_u32_e32 v137, s35, v134
	v_cndmask_b32_e32 v134, v134, v137, vcc
	v_cmp_le_u32_e32 vcc, s35, v134
	v_add_u32_e32 v134, 1, v135
	v_xor_b32_e32 v136, s36, v133
	v_cndmask_b32_e32 v134, v135, v134, vcc
	v_xor_b32_e32 v134, v134, v136
	v_sub_u32_e32 v137, v134, v136
	v_mul_lo_u32 v134, v137, s2
	v_sub_u32_e32 v139, v132, v134
	v_cmp_gt_i32_e32 vcc, s1, v139
	s_and_saveexec_b64 s[10:11], vcc
	v_readlane_b32 s42, v254, 38
	v_readlane_b32 s43, v254, 39
	s_cbranch_execz .LBB0_926
	v_readlane_b32 s12, v254, 29
	v_readlane_b32 s13, v254, 30
	v_cmp_lt_i32_e64 s[6:7], 15, v139
	s_andn2_b64 vcc, exec, s[12:13]
	s_mov_b64 s[12:13], -1
	s_cbranch_vccnz .LBB0_923
	s_and_saveexec_b64 s[12:13], s[6:7]
	s_xor_b64 s[12:13], exec, s[12:13]
	v_add_u32_e32 v184, -16, v139
	v_mad_i64_i32 v[134:135], s[14:15], v137, s34, v[184:185]
	v_lshlrev_b64 v[134:135], 13, v[134:135]
	v_lshl_add_u64 v[134:135], s[90:91], 0, v[134:135]
	s_andn2_saveexec_b64 s[12:13], s[12:13]
	s_cbranch_execz .LBB0_922
	v_readlane_b32 s14, v254, 36
	v_readlane_b32 s15, v254, 37
	s_load_dwordx16 s[44:59], s[14:15], 0xf8
	v_lshlrev_b32_e32 v134, 11, v139
	v_ashrrev_i32_e32 v135, 31, v134
	s_waitcnt lgkmcnt(0)
	v_lshl_add_u64 v[134:135], v[134:135], 2, s[54:55]

; #define MFMA(a, b, c) __builtin_amdgcn_mfma_f32_32x32x16_bf16((a), (b), (c), 0, 0, 0)
; template <bool SWAP, bool SSQ, class AF>
; DI void gemm_main(AF asrc, int m0, const u16* __restrict__ Bw, int ldb, int K, char* smem,
;                   f32x16 (&acc)[4][2], float ssq_eps, float (&rs)[4]) {
;     ...
;     {
;       bf16x8 ar[3], br[2][2];
;       ar[0] = *(const bf16x8*)(pA);
;       ar[1] = *(const bf16x8*)(pA + 32 * 144);
;       br[0][0] = *(const bf16x8*)(pB);
;       br[0][1] = *(const bf16x8*)(pB + 32 * 144);
;       __builtin_amdgcn_sched_group_barrier(0x100, 4, 0);
; #pragma unroll
;       for (int t = 0; t < 16; ++t) {
;         const int ks = t >> 2, mi = t & 3;
;         if (t + 2 < 16) {
;           ar[(t + 2) % 3] = *(const bf16x8*)(pA + ((t + 2) & 3) * (32 * 144) + ((t + 2) >> 2) * 32);
;           if (mi == 1 && ks + 1 < 4) {
;             br[(ks + 1) & 1][0] = *(const bf16x8*)(pB + (ks + 1) * 32);
;             br[(ks + 1) & 1][1] = *(const bf16x8*)(pB + 32 * 144 + (ks + 1) * 32);
;             __builtin_amdgcn_sched_group_barrier(0x100, 3, 0);
;           } else {
;             __builtin_amdgcn_sched_group_barrier(0x100, 1, 0);
;           }
;         }
;         acc[mi][0] = SWAP ? MFMA(br[ks & 1][0], ar[t % 3], acc[mi][0]) : MFMA(ar[t % 3], br[ks & 1][0], acc[mi][0]);
;         acc[mi][1] = SWAP ? MFMA(br[ks & 1][1], ar[t % 3], acc[mi][1]) : MFMA(ar[t % 3], br[ks & 1][1], acc[mi][1]);
;         __builtin_amdgcn_sched_group_barrier(0x008, 2, 0);
;         if (SSQ) {
;           u32x4 u = __builtin_bit_cast(u32x4, ar[t % 3]);
; #pragma unroll
;           for (int j = 0; j < 4; ++j) rs[mi] = dot2bf(u[j], rs[mi]);
;         }
;       }
;     }
;     __syncthreads();
;     if (kt + 1 < nkt) sstore();
;     __syncthreads();
; DI void phase_outproj(const Params& p, const GroupP& g, int l, char* smem, int vb) {
;     ...
;     for (int mi = 0; mi < 4; ++mi) {
;       int m = m0 + wm * 128 + mi * 32 + lr;
;       int b = m / g.Lp, t = m - b * g.Lp;
;       if (t >= g.L) continue;
;       if (l == 0) {
;         const float* res = (t < 16) ? p.meta + t * DM : g.x + ((long)b * (g.L - 16) + (t - 16)) * DM;
;         u16* dst = g.h1b + (long)m * DM;
.LBB0_973:
	ds_read_b128 v[140:143], v135 offset:36864
	ds_read_b128 v[152:155], v135 offset:41472
	ds_read_b128 v[144:147], v133
	ds_read_b128 v[148:151], v133 offset:4608
	ds_read_b128 v[156:159], v133 offset:9216
	v_add_u32_e32 v132, s8, v129
	s_or_b32 s8, s6, s33
	s_waitcnt lgkmcnt(2)
	v_mfma_f32_32x32x16_bf16 v[112:127], v[140:143], v[144:147], v[112:127]
	v_mfma_f32_32x32x16_bf16 v[96:111], v[152:155], v[144:147], v[96:111]
	ds_read_b128 v[160:163], v135 offset:36896
	ds_read_b128 v[164:167], v135 offset:41504
	ds_read_b128 v[144:147], v133 offset:13824
	s_waitcnt lgkmcnt(4)
	v_mfma_f32_32x32x16_bf16 v[80:95], v[140:143], v[148:151], v[80:95]
	v_mfma_f32_32x32x16_bf16 v[64:79], v[152:155], v[148:151], v[64:79]
	ds_read_b128 v[148:151], v133 offset:32
	s_waitcnt lgkmcnt(4)
	v_mfma_f32_32x32x16_bf16 v[48:63], v[140:143], v[156:159], v[48:63]
	v_mfma_f32_32x32x16_bf16 v[32:47], v[152:155], v[156:159], v[32:47]
	ds_read_b128 v[156:159], v133 offset:4640
	s_waitcnt lgkmcnt(2)
	v_mfma_f32_32x32x16_bf16 v[0:15], v[152:155], v[144:147], v[0:15]
	v_mfma_f32_32x32x16_bf16 v[16:31], v[140:143], v[144:147], v[16:31]
	ds_read_b128 v[140:143], v133 offset:9248
	s_waitcnt lgkmcnt(2)
	v_mfma_f32_32x32x16_bf16 v[112:127], v[160:163], v[148:151], v[112:127]
	v_mfma_f32_32x32x16_bf16 v[96:111], v[164:167], v[148:151], v[96:111]
	ds_read_b128 v[148:151], v135 offset:36928
	ds_read_b128 v[152:155], v135 offset:41536
	ds_read_b128 v[144:147], v133 offset:13856
	s_waitcnt lgkmcnt(4)
	v_mfma_f32_32x32x16_bf16 v[80:95], v[160:163], v[156:159], v[80:95]
	v_mfma_f32_32x32x16_bf16 v[64:79], v[164:167], v[156:159], v[64:79]
	ds_read_b128 v[156:159], v133 offset:64
	s_waitcnt lgkmcnt(4)
	v_mfma_f32_32x32x16_bf16 v[48:63], v[160:163], v[140:143], v[48:63]
	v_mfma_f32_32x32x16_bf16 v[32:47], v[164:167], v[140:143], v[32:47]
	ds_read_b128 v[140:143], v133 offset:4672
	s_waitcnt lgkmcnt(2)
	v_mfma_f32_32x32x16_bf16 v[0:15], v[164:167], v[144:147], v[0:15]
	v_mfma_f32_32x32x16_bf16 v[16:31], v[160:163], v[144:147], v[16:31]
	ds_read_b128 v[144:147], v133 offset:9280
	s_waitcnt lgkmcnt(2)
	v_mfma_f32_32x32x16_bf16 v[112:127], v[148:151], v[156:159], v[112:127]
	v_mfma_f32_32x32x16_bf16 v[96:111], v[152:155], v[156:159], v[96:111]
	ds_read_b128 v[160:163], v135 offset:36960
	ds_read_b128 v[134:137], v135 offset:41568
	ds_read_b128 v[156:159], v133 offset:13888
	s_waitcnt lgkmcnt(4)
	v_mfma_f32_32x32x16_bf16 v[80:95], v[148:151], v[140:143], v[80:95]
	v_mfma_f32_32x32x16_bf16 v[64:79], v[152:155], v[140:143], v[64:79]
	ds_read_b128 v[140:143], v133 offset:96
	s_waitcnt lgkmcnt(4)
	v_mfma_f32_32x32x16_bf16 v[48:63], v[148:151], v[144:147], v[48:63]
	v_mfma_f32_32x32x16_bf16 v[32:47], v[152:155], v[144:147], v[32:47]
	ds_read_b128 v[144:147], v133 offset:4704
	s_waitcnt lgkmcnt(2)
	v_mfma_f32_32x32x16_bf16 v[0:15], v[152:155], v[156:159], v[0:15]
	v_mfma_f32_32x32x16_bf16 v[16:31], v[148:151], v[156:159], v[16:31]
	ds_read_b128 v[148:151], v133 offset:9312
	s_waitcnt lgkmcnt(2)
	v_mfma_f32_32x32x16_bf16 v[112:127], v[160:163], v[140:143], v[112:127]
	v_mfma_f32_32x32x16_bf16 v[96:111], v[134:137], v[140:143], v[96:111]
	ds_read_b128 v[140:143], v133 offset:13920
	v_ashrrev_i32_e32 v133, 31, v132
	s_waitcnt lgkmcnt(0)
	s_barrier
	s_nop 0
	v_mfma_f32_32x32x16_bf16 v[80:95], v[160:163], v[144:147], v[80:95]
	v_mfma_f32_32x32x16_bf16 v[64:79], v[134:137], v[144:147], v[64:79]
	v_mfma_f32_32x32x16_bf16 v[48:63], v[160:163], v[148:151], v[48:63]
	v_mfma_f32_32x32x16_bf16 v[32:47], v[134:137], v[148:151], v[32:47]
	v_mfma_f32_32x32x16_bf16 v[0:15], v[134:137], v[140:143], v[0:15]
	v_sub_u32_e32 v134, 0, v132
	v_max_i32_e32 v134, v132, v134
	v_mul_hi_u32 v135, v134, v138
	v_mul_lo_u32 v137, v135, s36
	v_sub_u32_e32 v134, v134, v137
	v_cmp_le_u32_e32 vcc, s36, v134
	v_add_u32_e32 v137, 1, v135
	v_mfma_f32_32x32x16_bf16 v[16:31], v[160:163], v[140:143], v[16:31]
	v_cndmask_b32_e32 v135, v135, v137, vcc
	v_subrev_u32_e32 v137, s36, v134
	v_cndmask_b32_e32 v134, v134, v137, vcc
	v_cmp_le_u32_e32 vcc, s36, v134
	v_add_u32_e32 v134, 1, v135
	v_xor_b32_e32 v136, s37, v133
	v_cndmask_b32_e32 v134, v135, v134, vcc
	v_xor_b32_e32 v134, v134, v136
	v_sub_u32_e32 v137, v134, v136
	v_mul_lo_u32 v134, v137, s82
	v_sub_u32_e32 v139, v132, v134
	v_cmp_gt_i32_e32 vcc, s81, v139
	s_and_saveexec_b64 s[10:11], vcc
	s_cbranch_execz .LBB0_983
	v_readlane_b32 s12, v254, 29
	v_readlane_b32 s13, v254, 30
	v_cmp_lt_i32_e64 s[6:7], 15, v139
	s_andn2_b64 vcc, exec, s[12:13]
	s_mov_b64 s[12:13], -1
	s_cbranch_vccnz .LBB0_980
	s_and_saveexec_b64 s[12:13], s[6:7]
	s_xor_b64 s[12:13], exec, s[12:13]
	v_add_u32_e32 v184, -16, v139
	v_mad_i64_i32 v[134:135], s[14:15], v137, s35, v[184:185]
	v_lshlrev_b64 v[134:135], 13, v[134:135]
	v_lshl_add_u64 v[134:135], s[76:77], 0, v[134:135]
	s_andn2_saveexec_b64 s[12:13], s[12:13]
	s_cbranch_execz .LBB0_979
	v_readlane_b32 s14, v254, 36
	v_readlane_b32 s15, v254, 37
	s_load_dwordx16 s[44:59], s[14:15], 0xf8
	v_lshlrev_b32_e32 v134, 11, v139
	v_ashrrev_i32_e32 v135, 31, v134
	s_waitcnt lgkmcnt(0)
	v_lshl_add_u64 v[134:135], v[134:135], 2, s[54:55]
